# P3 scan beta LDS-read pipelining + P5 epilogue de-serialised (batched x loads, single ssq/fg load, no per-store waits)
# baseline (speedup 1.0000x reference)
.LBB0_349:
	s_lshr_b32 s34, s16, 6
	s_and_b64 s[18:19], exec, s[38:39]
	s_cselect_b32 s7, 0, 0x4000000
	s_add_u32 s7, s24, s7
	s_addc_u32 s9, s25, 0
	s_ashr_i32 s11, s10, 31
	s_lshl_b64 s[18:19], s[10:11], 20
	s_add_u32 s43, s7, s18
	s_addc_u32 s63, s9, s19
	s_and_b64 s[44:45], exec, s[38:39]
	s_cselect_b32 s7, s59, 0x6000000
	s_add_u32 s7, s24, s7
	s_addc_u32 s9, s25, 0
	s_add_u32 s64, s7, s18
	s_addc_u32 s65, s9, s19
	s_lshl_b64 s[14:15], s[14:15], 1
	s_add_u32 s46, s51, s14
	s_addc_u32 s47, s52, s15
	s_lshl_b32 s7, s10, 7
	s_lshl_b32 s9, s17, 6
	s_or_b32 s10, s7, s9
	s_ashr_i32 s11, s10, 31
	s_lshl_b64 s[10:11], s[10:11], 10
	s_ashr_i32 s31, s30, 31
	s_add_u32 s48, s33, s10
	s_addc_u32 s49, s50, s11
	s_lshr_b32 s18, s16, 7
	s_lshl_b64 s[10:11], s[30:31], 7
	s_bfe_u32 s31, s16, 0x20006
	s_and_b32 s66, s18, 0x1fffffe
	s_lshl_b32 s7, s12, 13
	s_lshl_b32 s9, s12, 14
	s_add_u32 s14, s43, s9
	s_addc_u32 s15, s63, 0
	v_lshl_add_u64 v[0:1], s[14:15], 0, v[120:121]
	s_add_u32 s16, s64, s9
	v_add_co_u32_e32 v0, vcc, s60, v0
	s_addc_u32 s17, s65, 0
	s_nop 0
	v_addc_co_u32_e32 v1, vcc, 0, v1, vcc
	v_lshl_add_u64 v[2:3], s[16:17], 0, v[120:121]
	v_add_co_u32_e32 v2, vcc, s60, v2
	global_load_dwordx4 v[56:59], v120, s[14:15]
	global_load_dwordx4 v[60:63], v120, s[16:17]
	v_addc_co_u32_e32 v3, vcc, 0, v3, vcc
	global_load_dwordx4 v[64:67], v[0:1], off
	global_load_dwordx4 v[68:71], v[2:3], off
	s_add_u32 s14, s46, s7
	s_addc_u32 s15, s47, 0
	global_load_dwordx4 v[72:75], v120, s[14:15]
	s_lshl_b32 s7, s12, 10
	s_add_u32 s12, s48, s7
	s_addc_u32 s13, s49, 0
	global_load_dwordx4 v[76:79], v142, s[12:13]
	global_load_dwordx4 v[0:3], v[126:127], off
	global_load_dwordx4 v[4:7], v[126:127], off offset:16
	global_load_dwordx4 v[8:11], v[128:129], off
	global_load_dwordx4 v[12:15], v[128:129], off offset:16
	global_load_dwordx4 v[16:19], v[130:131], off
	global_load_dwordx4 v[20:23], v[130:131], off offset:16
	global_load_dwordx4 v[24:27], v[132:133], off
	global_load_dwordx4 v[28:31], v[132:133], off offset:16
	s_waitcnt vmcnt(34)
	v_add_u32_e32 v32, 0, v154
	v_or_b32_e32 v144, s10, v122
	v_mov_b32_e32 v33, v121
	s_waitcnt vmcnt(20)
	v_add_u32_e32 v82, 0x1e400, v32
	v_and_b32_e32 v32, 0xf87, v144
	v_cmp_ne_u64_e32 vcc, 0, v[32:33]
	s_lshl_b32 s7, s8, 13
	s_lshl_b32 s9, s8, 14
	v_cndmask_b32_e64 v32, 0, 1, vcc
	s_add_u32 s10, s43, s9
	v_mov_b32_e32 v145, s11
	v_mov_b32_e32 v34, s11
	v_sub_co_u32_e32 v80, vcc, v144, v32
	s_addc_u32 s11, s63, 0
	s_nop 0
	v_subbrev_co_u32_e32 v81, vcc, 0, v34, vcc
	v_lshl_add_u64 v[36:37], s[10:11], 0, v[120:121]
	global_load_dwordx4 v[32:35], v120, s[10:11]
	s_add_u32 s10, s64, s9
	v_add_co_u32_e32 v36, vcc, s60, v36
	s_addc_u32 s11, s65, 0
	s_nop 0
	v_addc_co_u32_e32 v37, vcc, 0, v37, vcc
	v_lshl_add_u64 v[38:39], s[10:11], 0, v[120:121]
	s_add_u32 s12, s46, s7
	v_add_co_u32_e32 v40, vcc, s60, v38
	s_addc_u32 s13, s47, 0
	s_lshl_b32 s7, s8, 10
	v_addc_co_u32_e32 v41, vcc, 0, v39, vcc
	s_add_u32 s8, s48, s7
	global_load_dwordx4 v[36:39], v[36:37], off
	s_nop 0
	global_load_dwordx4 v[44:47], v[40:41], off
	s_nop 0
	global_load_dwordx4 v[40:43], v120, s[10:11]
	global_load_dwordx4 v[48:51], v120, s[12:13]
	s_addc_u32 s9, s49, 0
	s_lshl_b32 s7, s6, 13
	s_lshl_b32 s10, s6, 14
	global_load_dwordx4 v[52:55], v142, s[8:9]
	s_add_u32 s8, s43, s10
	s_addc_u32 s9, s63, 0
	s_add_u32 s10, s64, s10
	s_addc_u32 s11, s65, 0
	s_mul_i32 s67, s31, 0x1100
	v_add_u32_e32 v170, s67, v155
	v_lshl_or_b32 v173, s66, 4, v123
	v_mul_lo_u32 v174, v173, s3
	s_mov_b32 s44, 0
	s_mov_b32 s45, s44
	v_mov_b32_e32 v143, v121
	v_lshl_add_u32 v178, s34, 5, v160
	v_add_u32_e32 v181, 0xf000, v178
	v_add_u32_e32 v183, s67, v157
	s_waitcnt vmcnt(19)
	ds_write_b128 v168, v[56:59]
	s_waitcnt vmcnt(17)
	ds_write_b128 v168, v[64:67] offset:8704
	ds_write_b128 v168, v[60:63] offset:17408
	s_waitcnt vmcnt(16)
	ds_write_b128 v168, v[68:71] offset:26112
	s_waitcnt vmcnt(15)
	ds_write_b128 v169, v[72:75] offset:34816
	s_waitcnt vmcnt(14)
	ds_write_b128 v82, v[76:79]
	v_lshlrev_b64 v[56:57], 11, v[80:81]
	v_lshlrev_b64 v[64:65], 11, v[144:145]
	v_lshl_add_u64 v[72:73], s[8:9], 0, v[120:121]
	v_lshl_add_u64 v[56:57], v[134:135], 0, v[56:57]
	v_lshl_add_u64 v[66:67], v[134:135], 0, v[64:65]
	v_lshl_add_u64 v[68:69], v[136:137], 0, v[64:65]
	v_add_co_u32_e32 v80, vcc, s60, v72
	global_load_dwordx4 v[56:59], v[56:57], off
	s_nop 0
	global_load_dwordx4 v[60:63], v[66:67], off
	s_nop 0
	global_load_dwordx4 v[64:67], v[66:67], off offset:2048
	s_nop 0
	global_load_dwordx4 v[68:71], v[68:69], off
	v_addc_co_u32_e32 v81, vcc, 0, v73, vcc
	global_load_dwordx4 v[72:75], v120, s[8:9]
	global_load_dwordx4 v[76:79], v120, s[10:11]
	s_add_u32 s8, s46, s7
	v_lshl_add_u64 v[82:83], s[10:11], 0, v[120:121]
	s_addc_u32 s9, s47, 0
	s_lshl_b32 s6, s6, 10
	v_add_co_u32_e32 v84, vcc, s60, v82
	s_add_u32 s6, s48, s6
	s_nop 0
	v_addc_co_u32_e32 v85, vcc, 0, v83, vcc
	s_addc_u32 s7, s49, 0
	global_load_dwordx4 v[80:83], v[80:81], off
	s_nop 0
	global_load_dwordx4 v[84:87], v[84:85], off
	s_lshl_b32 s12, s18, 4
	global_load_dwordx4 v[88:91], v120, s[8:9]
	global_load_dwordx4 v[92:95], v142, s[6:7]
	s_waitcnt lgkmcnt(0)
	s_barrier
	ds_read_b128 v[96:99], v170 offset:17408
	s_mul_i32 s6, s66, 0x1100
	v_add_u32_e32 v171, s6, v155
	ds_read_b128 v[100:103], v171
	s_or_b32 s68, s12, 16
	ds_read_b128 v[104:107], v170 offset:17472
	ds_read_b128 v[108:111], v171 offset:64
	s_mul_i32 s6, s68, 0x110
	s_waitcnt lgkmcnt(2)
	v_mfma_f32_16x16x32_bf16 v[100:103], v[96:99], v[100:103], 0
	v_add_u32_e32 v172, s6, v155
	ds_read_b128 v[112:115], v172
	ds_read_b128 v[116:119], v172 offset:64
	v_or_b32_e32 v179, s68, v123
	s_waitcnt lgkmcnt(2)
	v_mfma_f32_16x16x32_bf16 v[100:103], v[104:107], v[108:111], v[100:103]
	ds_read_b128 v[108:111], v170 offset:17536
	v_mov_b32_e32 v184, v165
	v_mov_b64_e32 v[152:153], v[140:141]
	s_waitcnt lgkmcnt(2)
	v_mfma_f32_16x16x32_bf16 v[96:99], v[96:99], v[112:115], 0
	s_waitcnt lgkmcnt(1)
	v_mfma_f32_16x16x32_bf16 v[96:99], v[104:107], v[116:119], v[96:99]
	ds_read_b128 v[104:107], v171 offset:128
	ds_read_b128 v[112:115], v170 offset:17600
	ds_read_b128 v[116:119], v171 offset:192
	s_waitcnt lgkmcnt(2)
	v_mfma_f32_16x16x32_bf16 v[100:103], v[108:111], v[104:107], v[100:103]
	ds_read_b128 v[104:107], v172 offset:128
	ds_read_b128 v[146:149], v172 offset:192
	s_waitcnt lgkmcnt(1)
	v_mfma_f32_16x16x32_bf16 v[96:99], v[108:111], v[104:107], v[96:99]
	v_lshl_or_b32 v104, s31, 4, v124
	v_or_b32_e32 v107, 2, v104
	v_or_b32_e32 v108, 3, v104
	v_mfma_f32_16x16x32_bf16 v[100:103], v[112:115], v[116:119], v[100:103]
	v_cmp_gt_u32_e32 vcc, v104, v173
	v_cmp_ge_u32_e64 s[6:7], v104, v173
	v_cmp_gt_u32_e64 s[8:9], v107, v173
	v_cmp_gt_u32_e64 s[10:11], v108, v173
	v_lshlrev_b32_e32 v105, 1, v104
	s_xor_b64 vcc, s[38:39], vcc
	s_xor_b64 s[6:7], s[38:39], s[6:7]
	s_xor_b64 s[8:9], s[38:39], s[8:9]
	s_xor_b64 s[10:11], s[38:39], s[10:11]
	v_add_u32_e32 v106, s57, v105
	v_cndmask_b32_e32 v100, 0, v100, vcc
	v_cndmask_b32_e64 v101, 0, v101, s[6:7]
	v_cndmask_b32_e64 v102, 0, v102, s[8:9]
	v_cndmask_b32_e64 v103, 0, v103, s[10:11]
	s_waitcnt lgkmcnt(0)
	v_mfma_f32_16x16x32_bf16 v[96:99], v[112:115], v[146:149], v[96:99]
	v_cvt_pk_bf16_f32 v100, v100, v101
	v_cvt_pk_bf16_f32 v101, v102, v103
	v_add_u32_e32 v175, v106, v174
	ds_write_b64 v175, v[100:101]
	v_or_b32_e32 v100, s12, v164
	v_cmp_gt_u32_e64 s[12:13], v104, v100
	v_cmp_ge_u32_e64 s[14:15], v104, v100
	v_cmp_gt_u32_e64 s[16:17], v107, v100
	v_cmp_gt_u32_e64 s[18:19], v108, v100
	s_xor_b64 s[12:13], s[38:39], s[12:13]
	s_xor_b64 s[14:15], s[38:39], s[14:15]
	s_xor_b64 s[16:17], s[38:39], s[16:17]
	s_xor_b64 s[18:19], s[38:39], s[18:19]
	v_cndmask_b32_e64 v96, 0, v96, s[12:13]
	v_cndmask_b32_e64 v97, 0, v97, s[14:15]
	v_cndmask_b32_e64 v98, 0, v98, s[16:17]
	v_cndmask_b32_e64 v99, 0, v99, s[18:19]
	v_mul_lo_u32 v176, v100, s3
	v_cvt_pk_bf16_f32 v96, v96, v97
	v_cvt_pk_bf16_f32 v97, v98, v99
	v_add_u32_e32 v177, v106, v176
	ds_write_b64 v177, v[96:97]
	v_mov_b64_e32 v[96:97], s[44:45]
	global_store_dwordx2 v[138:139], v[96:97], off
	global_store_dwordx2 v[138:139], v[96:97], off
	global_store_dwordx2 v[138:139], v[96:97], off
	global_store_dwordx2 v[138:139], v[96:97], off
	global_store_dwordx2 v[138:139], v[96:97], off
	s_lshl_b32 s31, s31, 5
	global_store_dwordx2 v[138:139], v[96:97], off
	v_lshl_or_b32 v96, s34, 4, v124
	s_add_u32 s20, s20, s31
	s_waitcnt lgkmcnt(0)
	v_lshl_add_u64 v[148:149], s[48:49], 0, v[142:143]
	v_lshlrev_b32_e32 v143, 2, v96
	v_lshlrev_b32_e32 v98, 1, v96
	s_addc_u32 s21, s21, 0
	v_lshlrev_b32_e32 v96, 1, v124
	v_mov_b32_e32 v97, v121
	v_lshl_add_u64 v[150:151], s[20:21], 0, v[96:97]
	v_mov_b32_e32 v100, 0
	v_mov_b32_e32 v96, 1.0
	v_lshl_add_u64 v[146:147], s[46:47], 0, v[120:121]
	s_mul_i32 s45, s66, 0x900
	s_mul_i32 s46, s68, 0x90
	v_add_u32_e32 v180, s58, v105
	s_mov_b32 s47, 62
	v_add_u32_e32 v182, v163, v98
	v_mov_b32_e32 v97, v96
	v_mov_b32_e32 v98, v96
	v_mov_b32_e32 v99, v96
	v_mov_b32_e32 v101, v100
	v_mov_b32_e32 v102, v100
	v_mov_b32_e32 v103, v100
	v_mov_b32_e32 v104, v100
	v_mov_b32_e32 v105, v100
	v_mov_b32_e32 v106, v100
	v_mov_b32_e32 v107, v100
	v_mov_b32_e32 v108, v100
	v_mov_b32_e32 v109, v100
	v_mov_b32_e32 v110, v100
	v_mov_b32_e32 v111, v100
	v_mov_b32_e32 v112, v100
	v_mov_b32_e32 v113, v100
	v_mov_b32_e32 v114, v100
	v_mov_b32_e32 v115, v100
	v_add_u32_e32 v206, s31, v161
	v_add_u32_e32 v207, s31, v162
	v_add_u32_e32 v208, s45, v156
	v_add_u32_e32 v209, s46, v156
	v_add_u32_e32 v210, s45, v159
	v_add_u32_e32 v211, s46, v159
	v_add_u32_e32 v212, v180, v174
	v_add_u32_e32 v213, v180, v176
.LBB0_350:
	s_add_i32 s34, s47, 1
	s_and_b64 s[20:21], exec, s[38:39]
	s_cselect_b32 s48, s44, s34
	s_waitcnt vmcnt(20)
	ds_write_b128 v168, v[32:35] offset:44032
	s_waitcnt vmcnt(19)
	ds_write_b128 v168, v[36:39] offset:52736
	s_waitcnt vmcnt(18)
	ds_write_b128 v168, v[40:43] offset:61440
	s_waitcnt vmcnt(17)
	ds_write_b128 v166, v[44:47] offset:8704
	s_waitcnt vmcnt(16)
	ds_write_b128 v167, v[48:51]
	v_add_u32_e32 v32, s61, v154
	s_min_u32 s49, s44, 60
	s_waitcnt vmcnt(15)
	ds_write_b128 v32, v[52:55]
	v_add_u32_e32 v32, 0, v125
	s_add_i32 s34, s49, 3
	v_add_u32_e32 v186, 0x1ec00, v32
	v_add_u32_e32 v187, 0x20c00, v32
	v_add_u32_e32 v188, 0x22c00, v32
	v_add_u32_e32 v189, 0x24c00, v32
	v_sub_u32_e64 v32, 60, s44 clamp
	s_and_b64 s[20:21], exec, s[38:39]
	v_readfirstlane_b32 s20, v32
	s_cselect_b32 s66, s34, s20
	s_lshl_b32 s34, s66, 13
	s_lshl_b32 s67, s66, 14
	s_add_u32 s20, s43, s67
	s_addc_u32 s21, s63, 0
	v_lshl_add_u64 v[36:37], s[20:21], 0, v[120:121]
	global_load_dwordx4 v[32:35], v120, s[20:21]
	v_add_co_u32_e64 v36, s[20:21], s60, v36
	v_lshl_add_u64 v[48:49], v[146:147], 0, s[34:35]
	s_nop 0
	v_addc_co_u32_e64 v37, s[20:21], 0, v37, s[20:21]
	s_add_u32 s20, s64, s67
	s_addc_u32 s21, s65, 0
	v_lshl_add_u64 v[44:45], s[20:21], 0, v[120:121]
	global_load_dwordx4 v[36:39], v[36:37], off
	s_lshl_b32 s34, s66, 10
	global_load_dwordx4 v[40:43], v120, s[20:21]
	v_add_co_u32_e64 v44, s[20:21], s60, v44
	v_lshl_add_u64 v[52:53], v[148:149], 0, s[34:35]
	s_nop 0
	v_addc_co_u32_e64 v45, s[20:21], 0, v45, s[20:21]
	s_lshl_b32 s20, s49, 1
	s_add_i32 s34, s20, 4
	s_waitcnt vmcnt(15)
	ds_write_b128 v188, v[64:67]
	v_lshl_add_u64 v[64:65], v[144:145], 0, s[34:35]
	s_add_i32 s34, 0, 0x1e400
	ds_write_b128 v186, v[56:59]
	ds_write_b128 v187, v[60:63]
	s_waitcnt vmcnt(14)
	ds_write_b128 v189, v[68:71]
	v_add_u32_e32 v116, s34, v143
	ds_read_b128 v[190:193], v116
	v_and_b32_e32 v66, 0xfff, v64
	v_cmp_ne_u32_e64 s[20:21], 0, v66
	v_add_u32_e32 v185, 0, v143
	v_add_u32_e32 v116, 0x1e600, v185
	s_waitcnt lgkmcnt(0)
	v_pk_mul_f32 v[192:193], v[98:99], v[192:193]
	v_pk_mul_f32 v[190:191], v[96:97], v[190:191]
	v_pk_mul_f32 v[98:99], v[102:103], v[192:193]
	v_pk_mul_f32 v[96:97], v[100:101], v[190:191]
	v_cndmask_b32_e64 v56, 0, 1, s[20:21]
	v_cvt_pk_bf16_f32 v100, v96, v97
	v_cvt_pk_bf16_f32 v101, v98, v99
	v_sub_co_u32_e64 v56, s[20:21], v64, v56
	ds_read_b128 v[116:119], v116
	ds_write_b64 v182, v[100:101]
	v_pk_mul_f32 v[100:101], v[104:105], v[190:191]
	v_pk_mul_f32 v[102:103], v[106:107], v[192:193]
	v_subbrev_co_u32_e64 v57, s[20:21], 0, v65, s[20:21]
	v_cvt_pk_bf16_f32 v104, v100, v101
	v_cvt_pk_bf16_f32 v105, v102, v103
	v_cmp_ne_u32_e64 s[20:21], s62, v66
	ds_write_b64 v182, v[104:105] offset:4352
	v_pk_mul_f32 v[104:105], v[108:109], v[190:191]
	v_pk_mul_f32 v[106:107], v[110:111], v[192:193]
	v_cndmask_b32_e64 v66, 0, 1, s[20:21]
	v_mov_b32_e32 v67, s35
	v_cvt_pk_bf16_f32 v108, v104, v105
	v_cvt_pk_bf16_f32 v109, v106, v107
	v_lshlrev_b64 v[68:69], 11, v[64:65]
	v_lshl_add_u64 v[64:65], v[64:65], 0, v[66:67]
	ds_write_b64 v182, v[108:109] offset:8704
	v_pk_mul_f32 v[108:109], v[112:113], v[190:191]
	v_pk_mul_f32 v[110:111], v[114:115], v[192:193]
	v_lshlrev_b64 v[56:57], 11, v[56:57]
	v_lshlrev_b64 v[64:65], 11, v[64:65]
	v_cvt_pk_bf16_f32 v112, v108, v109
	v_cvt_pk_bf16_f32 v113, v110, v111
	v_lshl_add_u64 v[56:57], v[134:135], 0, v[56:57]
	v_lshl_add_u64 v[60:61], v[134:135], 0, v[68:69]
	v_lshl_add_u64 v[64:65], v[134:135], 0, v[64:65]
	v_lshl_add_u64 v[68:69], v[136:137], 0, v[68:69]
	ds_write_b64 v182, v[112:113] offset:13056
	global_load_dwordx4 v[44:47], v[44:45], off
	v_add_u32_e32 v198, s31, v161
	global_load_dwordx4 v[48:51], v[48:49], off
	v_add_u32_e32 v199, s45, v156
	global_load_dwordx4 v[52:55], v[52:53], off
	v_add_u32_e32 v202, s46, v156
	global_load_dwordx4 v[56:59], v[56:57], off
	s_lshl_b32 s48, s48, 6
	global_load_dwordx4 v[60:63], v[60:61], off
	s_nop 0
	global_load_dwordx4 v[64:67], v[64:65], off
	s_nop 0
	global_load_dwordx4 v[68:71], v[68:69], off
	s_waitcnt lgkmcnt(0)
	s_barrier
	ds_read_b128 v[198:201], v186
	ds_read_b128 v[202:205], v187
	ds_read_b128 v[214:217], v188
	ds_read_b128 v[242:245], v189
	ds_read_b128 v[218:221], v170 offset:61440
	ds_read_b128 v[222:225], v171 offset:44032
	ds_read_b128 v[226:229], v172 offset:44032
	ds_read_b64_tr_b16 v[230:231], v178 offset:17408
	ds_read_b64_tr_b16 v[232:233], v178 offset:18496
	ds_read_b64_tr_b16 v[234:235], v161 offset:34816
	ds_read_b64_tr_b16 v[236:237], v161 offset:35392
	ds_read_b64_tr_b16 v[238:239], v161 offset:34848
	ds_read_b64_tr_b16 v[240:241], v161 offset:35424
	v_and_b32_e32 v250, 0xfff, v184
	v_cmp_ne_u32_e64 s[20:21], 0, v250
	v_add_u32_e32 v184, 4, v184
	s_waitcnt lgkmcnt(9)
	v_cndmask_b32_e64 v198, 0, v198, s[20:21]
	v_cndmask_b32_e64 v199, 0, v199, s[20:21]
	v_cndmask_b32_e64 v200, 0, v200, s[20:21]
	v_cndmask_b32_e64 v201, 0, v201, s[20:21]
	v_cmp_ne_u32_e64 s[20:21], s62, v250
	v_lshlrev_b32_e32 v246, 16, v202
	v_and_b32_e32 v247, 0xffff0000, v202
	v_cndmask_b32_e64 v214, 0, v214, s[20:21]
	v_cndmask_b32_e64 v215, 0, v215, s[20:21]
	v_cndmask_b32_e64 v216, 0, v216, s[20:21]
	v_cndmask_b32_e64 v217, 0, v217, s[20:21]
	v_pk_mul_f32 v[246:247], v[8:9], v[246:247]
	v_lshlrev_b32_e32 v248, 16, v198
	v_and_b32_e32 v249, 0xffff0000, v198
	v_pk_fma_f32 v[246:247], v[0:1], v[248:249], v[246:247]
	v_lshlrev_b32_e32 v248, 16, v214
	v_and_b32_e32 v249, 0xffff0000, v214
	v_pk_fma_f32 v[246:247], v[16:17], v[248:249], v[246:247]
	v_pk_add_f32 v[246:247], v[24:25], v[246:247]
	v_lshlrev_b32_e32 v248, 16, v242
	v_and_b32_e32 v249, 0xffff0000, v242
	v_pk_mul_f32 v[246:247], v[246:247], v[248:249]
	v_cvt_pk_bf16_f32 v198, v246, v247
	v_lshlrev_b32_e32 v246, 16, v203
	v_and_b32_e32 v247, 0xffff0000, v203
	v_pk_mul_f32 v[246:247], v[10:11], v[246:247]
	v_lshlrev_b32_e32 v248, 16, v199
	v_and_b32_e32 v249, 0xffff0000, v199
	v_pk_fma_f32 v[246:247], v[2:3], v[248:249], v[246:247]
	v_lshlrev_b32_e32 v248, 16, v215
	v_and_b32_e32 v249, 0xffff0000, v215
	v_pk_fma_f32 v[246:247], v[18:19], v[248:249], v[246:247]
	v_pk_add_f32 v[246:247], v[26:27], v[246:247]
	v_lshlrev_b32_e32 v248, 16, v243
	v_and_b32_e32 v249, 0xffff0000, v243
	v_pk_mul_f32 v[246:247], v[246:247], v[248:249]
	v_cvt_pk_bf16_f32 v199, v246, v247
	v_lshlrev_b32_e32 v246, 16, v204
	v_and_b32_e32 v247, 0xffff0000, v204
	v_pk_mul_f32 v[246:247], v[12:13], v[246:247]
	v_lshlrev_b32_e32 v248, 16, v200
	v_and_b32_e32 v249, 0xffff0000, v200
	v_pk_fma_f32 v[246:247], v[4:5], v[248:249], v[246:247]
	v_lshlrev_b32_e32 v248, 16, v216
	v_and_b32_e32 v249, 0xffff0000, v216
	v_pk_fma_f32 v[246:247], v[20:21], v[248:249], v[246:247]
	v_pk_add_f32 v[246:247], v[28:29], v[246:247]
	v_lshlrev_b32_e32 v248, 16, v244
	v_and_b32_e32 v249, 0xffff0000, v244
	v_pk_mul_f32 v[246:247], v[246:247], v[248:249]
	v_cvt_pk_bf16_f32 v200, v246, v247
	v_lshlrev_b32_e32 v246, 16, v205
	v_and_b32_e32 v247, 0xffff0000, v205
	v_pk_mul_f32 v[246:247], v[14:15], v[246:247]
	v_lshlrev_b32_e32 v248, 16, v201
	v_and_b32_e32 v249, 0xffff0000, v201
	v_pk_fma_f32 v[246:247], v[6:7], v[248:249], v[246:247]
	v_lshlrev_b32_e32 v248, 16, v217
	v_and_b32_e32 v249, 0xffff0000, v217
	v_pk_fma_f32 v[246:247], v[22:23], v[248:249], v[246:247]
	v_pk_add_f32 v[246:247], v[30:31], v[246:247]
	v_lshlrev_b32_e32 v248, 16, v245
	v_and_b32_e32 v249, 0xffff0000, v245
	v_pk_mul_f32 v[246:247], v[246:247], v[248:249]
	v_cvt_pk_bf16_f32 v201, v246, v247
	global_store_dwordx4 v[152:153], v[198:201], off
	ds_read_b128 v[242:245], v170 offset:61504
	ds_read_b128 v[246:249], v171 offset:44096
	ds_read_b128 v[250:253], v172 offset:44096
	s_waitcnt lgkmcnt(9)
	v_mfma_f32_16x16x32_bf16 v[190:193], v[218:221], v[222:225], 0
	v_mfma_f32_16x16x32_bf16 v[194:197], v[218:221], v[226:229], 0
	ds_read_b64_tr_b16 v[218:219], v178 offset:17408
	ds_read_b64_tr_b16 v[220:221], v178 offset:18496
	ds_read_b64_tr_b16 v[222:223], v161 offset:34880
	ds_read_b64_tr_b16 v[224:225], v161 offset:35456
	ds_read_b64_tr_b16 v[226:227], v161 offset:34912
	ds_read_b64_tr_b16 v[228:229], v161 offset:35488
	s_waitcnt lgkmcnt(9)
	v_mfma_f32_16x16x32_bf16 v[96:99], v[230:233], v[234:237], v[96:99]
	v_mfma_f32_16x16x32_bf16 v[100:103], v[230:233], v[238:241], v[100:103]
	ds_read_b128 v[230:233], v170 offset:61568
	ds_read_b128 v[234:237], v171 offset:44160
	ds_read_b128 v[238:241], v172 offset:44160
	s_waitcnt lgkmcnt(9)
	v_mfma_f32_16x16x32_bf16 v[190:193], v[242:245], v[246:249], v[190:193]
	v_mfma_f32_16x16x32_bf16 v[194:197], v[242:245], v[250:253], v[194:197]
	ds_read_b64_tr_b16 v[242:243], v206 offset:34816
	ds_read_b64_tr_b16 v[244:245], v206 offset:35392
	ds_read_b128 v[246:249], v208
	ds_read_b128 v[250:253], v209
	s_waitcnt lgkmcnt(7)
	v_mfma_f32_16x16x32_bf16 v[104:107], v[218:221], v[222:225], v[104:107]
	v_mfma_f32_16x16x32_bf16 v[214:217], v[218:221], v[226:229], v[108:111]
	ds_read_b128 v[218:221], v170 offset:61632
	ds_read_b128 v[222:225], v171 offset:44224
	ds_read_b128 v[226:229], v172 offset:44224
	s_waitcnt lgkmcnt(7)
	v_mfma_f32_16x16x32_bf16 v[190:193], v[230:233], v[234:237], v[190:193]
	v_mfma_f32_16x16x32_bf16 v[194:197], v[230:233], v[238:241], v[194:197]
	ds_read_b64_tr_b16 v[230:231], v206 offset:39424
	ds_read_b64_tr_b16 v[232:233], v206 offset:40000
	ds_read_b128 v[234:237], v208 offset:64
	ds_read_b128 v[238:241], v209 offset:64
	s_waitcnt lgkmcnt(7)
	v_mfma_f32_16x16x32_bf16 v[198:201], v[242:245], v[246:249], 0
	v_mfma_f32_16x16x32_bf16 v[202:205], v[242:245], v[250:253], 0
	ds_read_b128 v[242:245], v183
	ds_read_b128 v[246:249], v171
	ds_read_b128 v[250:253], v172
	s_waitcnt lgkmcnt(7)
	v_mfma_f32_16x16x32_bf16 v[190:193], v[218:221], v[222:225], v[190:193]
	v_mfma_f32_16x16x32_bf16 v[194:197], v[218:221], v[226:229], v[194:197]
	ds_read_b128 v[218:221], v183 offset:64
	ds_read_b128 v[222:225], v171 offset:64
	ds_read_b128 v[226:229], v172 offset:64
	s_waitcnt lgkmcnt(6)
	v_mfma_f32_16x16x32_bf16 v[198:201], v[230:233], v[234:237], v[198:201]
	v_mfma_f32_16x16x32_bf16 v[202:205], v[230:233], v[238:241], v[202:205]
	ds_read_b128 v[230:233], v183 offset:128
	ds_read_b128 v[234:237], v171 offset:128
	ds_read_b128 v[238:241], v172 offset:128
	v_cndmask_b32_e32 v190, 0, v190, vcc
	v_cndmask_b32_e64 v191, 0, v191, s[6:7]
	v_cndmask_b32_e64 v192, 0, v192, s[8:9]
	v_cndmask_b32_e64 v193, 0, v193, s[10:11]
	v_cvt_pk_bf16_f32 v190, v190, v191
	v_cvt_pk_bf16_f32 v191, v192, v193
	v_cndmask_b32_e64 v194, 0, v194, s[12:13]
	v_cndmask_b32_e64 v195, 0, v195, s[14:15]
	v_cndmask_b32_e64 v196, 0, v196, s[16:17]
	v_cndmask_b32_e64 v197, 0, v197, s[18:19]
	v_cvt_pk_bf16_f32 v194, v194, v195
	v_cvt_pk_bf16_f32 v195, v196, v197
	ds_write_b64 v212, v[190:191]
	ds_write_b64 v213, v[194:195]
	s_waitcnt lgkmcnt(8)
	v_mfma_f32_16x16x32_bf16 v[198:201], v[242:245], v[246:249], v[198:201]
	v_mfma_f32_16x16x32_bf16 v[202:205], v[242:245], v[250:253], v[202:205]
	ds_read_b128 v[242:245], v183 offset:192
	ds_read_b128 v[246:249], v171 offset:192
	ds_read_b128 v[250:253], v172 offset:192
	s_waitcnt lgkmcnt(8)
	v_mfma_f32_16x16x32_bf16 v[198:201], v[218:221], v[222:225], v[198:201]
	v_mfma_f32_16x16x32_bf16 v[202:205], v[218:221], v[226:229], v[202:205]
	ds_read_b64_tr_b16 v[218:219], v178 offset:26112
	ds_read_b64_tr_b16 v[220:221], v178 offset:27200
	ds_read_b64_tr_b16 v[222:223], v161 offset:39424
	ds_read_b64_tr_b16 v[224:225], v161 offset:40000
	ds_read_b64_tr_b16 v[226:227], v161 offset:39456
	ds_read_b64_tr_b16 v[228:229], v161 offset:40032
	s_waitcnt lgkmcnt(11)
	v_mfma_f32_16x16x32_bf16 v[198:201], v[230:233], v[234:237], v[198:201]
	v_mfma_f32_16x16x32_bf16 v[202:205], v[230:233], v[238:241], v[202:205]
	ds_read_b64_tr_b16 v[230:231], v178 offset:26112
	ds_read_b64_tr_b16 v[232:233], v178 offset:27200
	ds_read_b64_tr_b16 v[234:235], v161 offset:39488
	ds_read_b64_tr_b16 v[236:237], v161 offset:40064
	ds_read_b64_tr_b16 v[238:239], v161 offset:39520
	ds_read_b64_tr_b16 v[240:241], v161 offset:40096
	s_waitcnt lgkmcnt(12)
	v_mfma_f32_16x16x32_bf16 v[198:201], v[242:245], v[246:249], v[198:201]
	v_mfma_f32_16x16x32_bf16 v[202:205], v[242:245], v[250:253], v[202:205]
	s_waitcnt lgkmcnt(6)
	v_mfma_f32_16x16x32_bf16 v[112:115], v[218:221], v[222:225], v[96:99]
	v_mfma_f32_16x16x32_bf16 v[108:111], v[218:221], v[226:229], v[100:103]
	s_nop 3
	v_cvt_pk_bf16_f32 v198, v198, v199
	v_cvt_pk_bf16_f32 v199, v200, v201
	v_add_u32_e32 v254, s48, v173
	v_mad_u64_u32 v[254:255], s[20:21], v254, s42, 0
	v_lshl_add_u64 v[254:255], v[254:255], 1, v[150:151]
	v_cvt_pk_bf16_f32 v202, v202, v203
	v_cvt_pk_bf16_f32 v203, v204, v205
	global_store_dwordx2 v[254:255], v[198:199], off
	v_add_u32_e32 v254, s48, v179
	v_mad_u64_u32 v[254:255], s[20:21], v254, s42, 0
	v_lshl_add_u64 v[254:255], v[254:255], 1, v[150:151]
	global_store_dwordx2 v[254:255], v[202:203], off
	s_waitcnt lgkmcnt(0)
	v_mfma_f32_16x16x32_bf16 v[104:107], v[230:233], v[234:237], v[104:107]
	v_mfma_f32_16x16x32_bf16 v[100:103], v[230:233], v[238:241], v[214:217]
	s_min_u32 s20, s44, 59
	s_waitcnt lgkmcnt(0)
	s_barrier
	s_waitcnt vmcnt(20)
	ds_write_b128 v168, v[72:75]
	s_waitcnt vmcnt(19)
	ds_write_b128 v168, v[80:83] offset:8704
	s_waitcnt vmcnt(18)
	ds_write_b128 v168, v[76:79] offset:17408
	s_waitcnt vmcnt(17)
	ds_write_b128 v168, v[84:87] offset:26112
	s_waitcnt vmcnt(16)
	ds_write_b128 v169, v[88:91] offset:34816
	v_add_u32_e32 v72, s34, v154
	s_add_i32 s34, s20, 4
	s_waitcnt vmcnt(15)
	ds_write_b128 v72, v[92:95]
	v_sub_u32_e64 v72, 59, s44 clamp
	s_and_b64 s[20:21], exec, s[38:39]
	v_readfirstlane_b32 s20, v72
	s_cselect_b32 s48, s34, s20
	v_add_u32_e32 v96, s61, v143
	s_lshl_b32 s34, s48, 13
	s_lshl_b32 s49, s48, 14
	ds_read_b128 v[186:189], v96
	s_add_u32 s20, s43, s49
	s_addc_u32 s21, s63, 0
	v_lshl_add_u64 v[76:77], s[20:21], 0, v[120:121]
	global_load_dwordx4 v[72:75], v120, s[20:21]
	v_add_co_u32_e64 v76, s[20:21], s60, v76
	s_waitcnt lgkmcnt(0)
	v_pk_mul_f32 v[118:119], v[118:119], v[188:189]
	v_addc_co_u32_e64 v77, s[20:21], 0, v77, s[20:21]
	v_pk_mul_f32 v[116:117], v[116:117], v[186:187]
	s_add_u32 s20, s64, s49
	v_pk_mul_f32 v[114:115], v[114:115], v[118:119]
	v_pk_mul_f32 v[112:113], v[112:113], v[116:117]
	s_addc_u32 s21, s65, 0
	v_add_u32_e32 v96, 0x1ea00, v185
	v_cvt_pk_bf16_f32 v186, v112, v113
	v_cvt_pk_bf16_f32 v187, v114, v115
	v_pk_mul_f32 v[110:111], v[110:111], v[118:119]
	v_pk_mul_f32 v[108:109], v[108:109], v[116:117]
	v_lshl_add_u64 v[84:85], s[20:21], 0, v[120:121]
	ds_read_b128 v[96:99], v96
	ds_write_b64 v182, v[186:187]
	v_cvt_pk_bf16_f32 v186, v108, v109
	v_cvt_pk_bf16_f32 v187, v110, v111
	v_pk_mul_f32 v[106:107], v[106:107], v[118:119]
	v_pk_mul_f32 v[104:105], v[104:105], v[116:117]
	v_pk_mul_f32 v[102:103], v[102:103], v[118:119]
	v_pk_mul_f32 v[100:101], v[100:101], v[116:117]
	global_load_dwordx4 v[80:83], v[76:77], off
	v_lshl_add_u64 v[88:89], v[146:147], 0, s[34:35]
	global_load_dwordx4 v[76:79], v120, s[20:21]
	v_add_co_u32_e64 v84, s[20:21], s60, v84
	s_lshl_b32 s34, s48, 10
	ds_write_b64 v182, v[186:187] offset:4352
	v_cvt_pk_bf16_f32 v186, v104, v105
	v_cvt_pk_bf16_f32 v187, v106, v107
	v_cvt_pk_bf16_f32 v116, v100, v101
	v_cvt_pk_bf16_f32 v117, v102, v103
	v_addc_co_u32_e64 v85, s[20:21], 0, v85, s[20:21]
	v_lshl_add_u64 v[92:93], v[148:149], 0, s[34:35]
	ds_write_b64 v182, v[186:187] offset:8704
	ds_write_b64 v182, v[116:117] offset:13056
	global_load_dwordx4 v[84:87], v[84:85], off
	v_add_u32_e32 v185, s31, v162
	global_load_dwordx4 v[88:91], v[88:89], off
	v_add_u32_e32 v194, s45, v159
	global_load_dwordx4 v[92:95], v[92:93], off
	s_waitcnt lgkmcnt(0)
	s_barrier
	ds_read_b128 v[218:221], v170 offset:17408
	ds_read_b128 v[222:225], v171
	ds_read_b128 v[226:229], v172
	ds_read_b64_tr_b16 v[230:231], v178 offset:61440
	ds_read_b64_tr_b16 v[232:233], v178 offset:62528
	ds_read_b64_tr_b16 v[234:235], v162
	ds_read_b64_tr_b16 v[236:237], v162 offset:576
	ds_read_b64_tr_b16 v[238:239], v162 offset:32
	ds_read_b64_tr_b16 v[240:241], v162 offset:608
	ds_read_b128 v[242:245], v170 offset:17472
	ds_read_b128 v[246:249], v171 offset:64
	ds_read_b128 v[250:253], v172 offset:64
	s_add_i32 s34, s44, 1
	s_and_b64 s[20:21], exec, s[38:39]
	s_cselect_b32 s20, s34, s47
	s_lshl_b32 s34, s20, 6
	s_add_i32 s47, s47, -2
	v_lshl_add_u64 v[152:153], v[152:153], 0, s[36:37]
	s_waitcnt lgkmcnt(9)
	v_mfma_f32_16x16x32_bf16 v[190:193], v[218:221], v[222:225], 0
	v_mfma_f32_16x16x32_bf16 v[194:197], v[218:221], v[226:229], 0
	ds_read_b64_tr_b16 v[218:219], v178 offset:61440
	ds_read_b64_tr_b16 v[220:221], v178 offset:62528
	ds_read_b64_tr_b16 v[222:223], v162 offset:64
	ds_read_b64_tr_b16 v[224:225], v162 offset:640
	ds_read_b64_tr_b16 v[226:227], v162 offset:96
	ds_read_b64_tr_b16 v[228:229], v162 offset:672
	s_waitcnt lgkmcnt(9)
	v_mfma_f32_16x16x32_bf16 v[112:115], v[230:233], v[234:237], v[112:115]
	v_mfma_f32_16x16x32_bf16 v[108:111], v[230:233], v[238:241], v[108:111]
	ds_read_b128 v[230:233], v170 offset:17536
	ds_read_b128 v[234:237], v171 offset:128
	ds_read_b128 v[238:241], v172 offset:128
	s_waitcnt lgkmcnt(9)
	v_mfma_f32_16x16x32_bf16 v[190:193], v[242:245], v[246:249], v[190:193]
	v_mfma_f32_16x16x32_bf16 v[194:197], v[242:245], v[250:253], v[194:197]
	ds_read_b64_tr_b16 v[242:243], v207
	ds_read_b64_tr_b16 v[244:245], v207 offset:576
	ds_read_b128 v[246:249], v210
	ds_read_b128 v[250:253], v211
	s_waitcnt lgkmcnt(7)
	v_mfma_f32_16x16x32_bf16 v[214:217], v[218:221], v[222:225], v[104:107]
	v_mfma_f32_16x16x32_bf16 v[116:119], v[218:221], v[226:229], v[100:103]
	ds_read_b128 v[218:221], v170 offset:17600
	ds_read_b128 v[222:225], v171 offset:192
	ds_read_b128 v[226:229], v172 offset:192
	s_waitcnt lgkmcnt(7)
	v_mfma_f32_16x16x32_bf16 v[190:193], v[230:233], v[234:237], v[190:193]
	v_mfma_f32_16x16x32_bf16 v[194:197], v[230:233], v[238:241], v[194:197]
	ds_read_b64_tr_b16 v[230:231], v207 offset:4608
	ds_read_b64_tr_b16 v[232:233], v207 offset:5184
	ds_read_b128 v[234:237], v210 offset:64
	ds_read_b128 v[238:241], v211 offset:64
	s_waitcnt lgkmcnt(7)
	v_mfma_f32_16x16x32_bf16 v[198:201], v[242:245], v[246:249], 0
	v_mfma_f32_16x16x32_bf16 v[202:205], v[242:245], v[250:253], 0
	ds_read_b128 v[242:245], v183
	ds_read_b128 v[246:249], v171 offset:44032
	ds_read_b128 v[250:253], v172 offset:44032
	s_waitcnt lgkmcnt(7)
	v_mfma_f32_16x16x32_bf16 v[190:193], v[218:221], v[222:225], v[190:193]
	v_mfma_f32_16x16x32_bf16 v[194:197], v[218:221], v[226:229], v[194:197]
	ds_read_b128 v[218:221], v183 offset:64
	ds_read_b128 v[222:225], v171 offset:44096
	ds_read_b128 v[226:229], v172 offset:44096
	s_waitcnt lgkmcnt(6)
	v_mfma_f32_16x16x32_bf16 v[198:201], v[230:233], v[234:237], v[198:201]
	v_mfma_f32_16x16x32_bf16 v[202:205], v[230:233], v[238:241], v[202:205]
	ds_read_b128 v[230:233], v183 offset:128
	ds_read_b128 v[234:237], v171 offset:44160
	ds_read_b128 v[238:241], v172 offset:44160
	v_cndmask_b32_e32 v190, 0, v190, vcc
	v_cndmask_b32_e64 v191, 0, v191, s[6:7]
	v_cndmask_b32_e64 v192, 0, v192, s[8:9]
	v_cndmask_b32_e64 v193, 0, v193, s[10:11]
	v_cvt_pk_bf16_f32 v190, v190, v191
	v_cvt_pk_bf16_f32 v191, v192, v193
	v_cndmask_b32_e64 v194, 0, v194, s[12:13]
	v_cndmask_b32_e64 v195, 0, v195, s[14:15]
	v_cndmask_b32_e64 v196, 0, v196, s[16:17]
	v_cndmask_b32_e64 v197, 0, v197, s[18:19]
	v_cvt_pk_bf16_f32 v194, v194, v195
	v_cvt_pk_bf16_f32 v195, v196, v197
	ds_write_b64 v175, v[190:191]
	ds_write_b64 v177, v[194:195]
	s_waitcnt lgkmcnt(8)
	v_mfma_f32_16x16x32_bf16 v[198:201], v[242:245], v[246:249], v[198:201]
	v_mfma_f32_16x16x32_bf16 v[202:205], v[242:245], v[250:253], v[202:205]
	ds_read_b128 v[242:245], v183 offset:192
	ds_read_b128 v[246:249], v171 offset:44224
	ds_read_b128 v[250:253], v172 offset:44224
	s_waitcnt lgkmcnt(8)
	v_mfma_f32_16x16x32_bf16 v[198:201], v[218:221], v[222:225], v[198:201]
	v_mfma_f32_16x16x32_bf16 v[202:205], v[218:221], v[226:229], v[202:205]
	ds_read_b64_tr_b16 v[218:219], v181 offset:8704
	ds_read_b64_tr_b16 v[220:221], v181 offset:9792
	ds_read_b64_tr_b16 v[222:223], v162 offset:4608
	ds_read_b64_tr_b16 v[224:225], v162 offset:5184
	ds_read_b64_tr_b16 v[226:227], v162 offset:4640
	ds_read_b64_tr_b16 v[228:229], v162 offset:5216
	s_waitcnt lgkmcnt(11)
	v_mfma_f32_16x16x32_bf16 v[198:201], v[230:233], v[234:237], v[198:201]
	v_mfma_f32_16x16x32_bf16 v[202:205], v[230:233], v[238:241], v[202:205]
	ds_read_b64_tr_b16 v[230:231], v181 offset:8704
	ds_read_b64_tr_b16 v[232:233], v181 offset:9792
	ds_read_b64_tr_b16 v[234:235], v162 offset:4672
	ds_read_b64_tr_b16 v[236:237], v162 offset:5248
	ds_read_b64_tr_b16 v[238:239], v162 offset:4704
	ds_read_b64_tr_b16 v[240:241], v162 offset:5280
	s_waitcnt lgkmcnt(12)
	v_mfma_f32_16x16x32_bf16 v[198:201], v[242:245], v[246:249], v[198:201]
	v_mfma_f32_16x16x32_bf16 v[202:205], v[242:245], v[250:253], v[202:205]
	s_waitcnt lgkmcnt(6)
	v_mfma_f32_16x16x32_bf16 v[100:103], v[218:221], v[222:225], v[112:115]
	v_mfma_f32_16x16x32_bf16 v[104:107], v[218:221], v[226:229], v[108:111]
	s_nop 3
	v_cvt_pk_bf16_f32 v198, v198, v199
	v_cvt_pk_bf16_f32 v199, v200, v201
	v_add_u32_e32 v254, s34, v173
	v_mad_u64_u32 v[254:255], s[20:21], v254, s42, 0
	v_lshl_add_u64 v[254:255], v[254:255], 1, v[150:151]
	v_cvt_pk_bf16_f32 v202, v202, v203
	v_cvt_pk_bf16_f32 v203, v204, v205
	global_store_dwordx2 v[254:255], v[198:199], off
	v_add_u32_e32 v254, s34, v179
	v_mad_u64_u32 v[254:255], s[20:21], v254, s42, 0
	v_lshl_add_u64 v[254:255], v[254:255], 1, v[150:151]
	global_store_dwordx2 v[254:255], v[202:203], off
	s_waitcnt lgkmcnt(0)
	v_mfma_f32_16x16x32_bf16 v[108:111], v[230:233], v[234:237], v[214:217]
	v_mfma_f32_16x16x32_bf16 v[112:115], v[230:233], v[238:241], v[116:119]
	s_add_i32 s20, s44, 2
	s_cmp_lt_u32 s44, 62
	s_mov_b32 s44, s20
	s_waitcnt lgkmcnt(0)
	s_barrier
	s_cbranch_scc1 .LBB0_350
	s_add_i32 s30, s30, s28
	v_lshl_add_u64 v[140:141], v[140:141], 0, s[26:27]
	s_cmpk_lt_i32 s30, 0x100
	v_add_u32_e32 v165, s29, v165
	s_cbranch_scc1 .LBB0_344

.LBB0_488:
	v_lshl_add_u32 v140, s8, 8, v162
	v_lshl_or_b32 v143, s42, 8, v164
	v_lshlrev_b32_e32 v142, 12, v140
	v_lshlrev_b32_e32 v143, 2, v143
	v_lshlrev_b32_e32 v141, 2, v140
	v_add_u32_e32 v142, v142, v143
	v_xor_b32_e32 v144, 16, v168
	v_xor_b32_e32 v145, 32, v168
	v_lshlrev_b32_e32 v144, 2, v144
	v_lshlrev_b32_e32 v145, 2, v145
	global_load_dwordx4 v[176:179], v142, s[16:17] nt
	global_load_dwordx4 v[180:183], v142, s[16:17] offset:64 nt
	global_load_dwordx4 v[184:187], v142, s[16:17] offset:512 nt
	global_load_dwordx4 v[188:191], v142, s[16:17] offset:576 nt
	s_add_u32 s100, s16, 0x10000
	s_addc_u32 s101, s17, 0
	global_load_dwordx4 v[192:195], v142, s[100:101] nt
	global_load_dwordx4 v[196:199], v142, s[100:101] offset:64 nt
	global_load_dwordx4 v[200:203], v142, s[100:101] offset:512 nt
	global_load_dwordx4 v[204:207], v142, s[100:101] offset:576 nt
	s_add_u32 s100, s16, 0x20000
	s_addc_u32 s101, s17, 0
	global_load_dwordx4 v[208:211], v142, s[100:101] nt
	global_load_dwordx4 v[212:215], v142, s[100:101] offset:64 nt
	global_load_dwordx4 v[216:219], v142, s[100:101] offset:512 nt
	global_load_dwordx4 v[220:223], v142, s[100:101] offset:576 nt
	s_add_u32 s100, s16, 0x30000
	s_addc_u32 s101, s17, 0
	global_load_dwordx4 v[224:227], v142, s[100:101] nt
	global_load_dwordx4 v[228:231], v142, s[100:101] offset:64 nt
	global_load_dwordx4 v[232:235], v142, s[100:101] offset:512 nt
	global_load_dwordx4 v[236:239], v142, s[100:101] offset:576 nt
	s_add_u32 s100, s16, 0x80000
	s_addc_u32 s101, s17, 0
	global_load_dwordx4 v[240:243], v142, s[100:101] nt
	global_load_dwordx4 v[244:247], v142, s[100:101] offset:64 nt
	global_load_dwordx4 v[248:251], v142, s[100:101] offset:512 nt
	global_load_dwordx4 v[252:255], v142, s[100:101] offset:576 nt
	s_waitcnt vmcnt(16)
	v_pk_add_f32 v[124:125], v[124:125], v[176:177]
	v_pk_add_f32 v[126:127], v[126:127], v[178:179]
	v_pk_add_f32 v[120:121], v[120:121], v[180:181]
	v_pk_add_f32 v[122:123], v[122:123], v[182:183]
	v_pk_add_f32 v[116:117], v[116:117], v[184:185]
	v_pk_add_f32 v[118:119], v[118:119], v[186:187]
	v_pk_add_f32 v[112:113], v[112:113], v[188:189]
	v_pk_add_f32 v[114:115], v[114:115], v[190:191]
	v_mul_f32_e32 v176, v125, v125
	v_mul_f32_e32 v177, v127, v127
	v_mul_f32_e32 v178, v121, v121
	v_mul_f32_e32 v179, v123, v123
	v_mul_f32_e32 v180, v117, v117
	v_mul_f32_e32 v181, v119, v119
	v_mul_f32_e32 v182, v113, v113
	v_mul_f32_e32 v183, v115, v115
	v_fmac_f32_e32 v176, v124, v124
	v_fmac_f32_e32 v177, v126, v126
	v_fmac_f32_e32 v178, v120, v120
	v_fmac_f32_e32 v179, v122, v122
	v_fmac_f32_e32 v180, v116, v116
	v_fmac_f32_e32 v181, v118, v118
	v_fmac_f32_e32 v182, v112, v112
	v_fmac_f32_e32 v183, v114, v114
	v_add_f32_e32 v176, v176, v177
	v_add_f32_e32 v178, v178, v179
	v_add_f32_e32 v180, v180, v181
	v_add_f32_e32 v176, v176, v178
	v_add_f32_e32 v176, v176, v180
	v_add_f32_e32 v182, v182, v183
	v_add_f32_e32 v146, v176, v182
	ds_bpermute_b32 v154, v144, v146
	s_add_u32 s100, s16, 0x90000
	s_addc_u32 s101, s17, 0
	global_load_dwordx4 v[176:179], v142, s[100:101] nt
	global_load_dwordx4 v[180:183], v142, s[100:101] offset:64 nt
	global_load_dwordx4 v[184:187], v142, s[100:101] offset:512 nt
	global_load_dwordx4 v[188:191], v142, s[100:101] offset:576 nt
	s_waitcnt vmcnt(16)
	v_pk_add_f32 v[108:109], v[108:109], v[192:193]
	v_pk_add_f32 v[110:111], v[110:111], v[194:195]
	v_pk_add_f32 v[104:105], v[104:105], v[196:197]
	v_pk_add_f32 v[106:107], v[106:107], v[198:199]
	v_pk_add_f32 v[100:101], v[100:101], v[200:201]
	v_pk_add_f32 v[102:103], v[102:103], v[202:203]
	v_pk_add_f32 v[96:97], v[96:97], v[204:205]
	v_pk_add_f32 v[98:99], v[98:99], v[206:207]
	v_mul_f32_e32 v192, v109, v109
	v_mul_f32_e32 v193, v111, v111
	v_mul_f32_e32 v194, v105, v105
	v_mul_f32_e32 v195, v107, v107
	v_mul_f32_e32 v196, v101, v101
	v_mul_f32_e32 v197, v103, v103
	v_mul_f32_e32 v198, v97, v97
	v_mul_f32_e32 v199, v99, v99
	v_fmac_f32_e32 v192, v108, v108
	v_fmac_f32_e32 v193, v110, v110
	v_fmac_f32_e32 v194, v104, v104
	v_fmac_f32_e32 v195, v106, v106
	v_fmac_f32_e32 v196, v100, v100
	v_fmac_f32_e32 v197, v102, v102
	v_fmac_f32_e32 v198, v96, v96
	v_fmac_f32_e32 v199, v98, v98
	v_add_f32_e32 v192, v192, v193
	v_add_f32_e32 v194, v194, v195
	v_add_f32_e32 v196, v196, v197
	v_add_f32_e32 v192, v192, v194
	v_add_f32_e32 v192, v192, v196
	v_add_f32_e32 v198, v198, v199
	v_add_f32_e32 v147, v192, v198
	ds_bpermute_b32 v155, v144, v147
	s_add_u32 s100, s16, 0xa0000
	s_addc_u32 s101, s17, 0
	global_load_dwordx4 v[192:195], v142, s[100:101] nt
	global_load_dwordx4 v[196:199], v142, s[100:101] offset:64 nt
	global_load_dwordx4 v[200:203], v142, s[100:101] offset:512 nt
	global_load_dwordx4 v[204:207], v142, s[100:101] offset:576 nt
	s_waitcnt vmcnt(16)
	v_pk_add_f32 v[92:93], v[92:93], v[208:209]
	v_pk_add_f32 v[94:95], v[94:95], v[210:211]
	v_pk_add_f32 v[88:89], v[88:89], v[212:213]
	v_pk_add_f32 v[90:91], v[90:91], v[214:215]
	v_pk_add_f32 v[84:85], v[84:85], v[216:217]
	v_pk_add_f32 v[86:87], v[86:87], v[218:219]
	v_pk_add_f32 v[80:81], v[80:81], v[220:221]
	v_pk_add_f32 v[82:83], v[82:83], v[222:223]
	v_mul_f32_e32 v208, v93, v93
	v_mul_f32_e32 v209, v95, v95
	v_mul_f32_e32 v210, v89, v89
	v_mul_f32_e32 v211, v91, v91
	v_mul_f32_e32 v212, v85, v85
	v_mul_f32_e32 v213, v87, v87
	v_mul_f32_e32 v214, v81, v81
	v_mul_f32_e32 v215, v83, v83
	v_fmac_f32_e32 v208, v92, v92
	v_fmac_f32_e32 v209, v94, v94
	v_fmac_f32_e32 v210, v88, v88
	v_fmac_f32_e32 v211, v90, v90
	v_fmac_f32_e32 v212, v84, v84
	v_fmac_f32_e32 v213, v86, v86
	v_fmac_f32_e32 v214, v80, v80
	v_fmac_f32_e32 v215, v82, v82
	v_add_f32_e32 v208, v208, v209
	v_add_f32_e32 v210, v210, v211
	v_add_f32_e32 v212, v212, v213
	v_add_f32_e32 v208, v208, v210
	v_add_f32_e32 v208, v208, v212
	v_add_f32_e32 v214, v214, v215
	v_add_f32_e32 v148, v208, v214
	ds_bpermute_b32 v156, v144, v148
	s_add_u32 s100, s16, 0xb0000
	s_addc_u32 s101, s17, 0
	global_load_dwordx4 v[208:211], v142, s[100:101] nt
	global_load_dwordx4 v[212:215], v142, s[100:101] offset:64 nt
	global_load_dwordx4 v[216:219], v142, s[100:101] offset:512 nt
	global_load_dwordx4 v[220:223], v142, s[100:101] offset:576 nt
	s_waitcnt vmcnt(16)
	v_pk_add_f32 v[76:77], v[76:77], v[224:225]
	v_pk_add_f32 v[78:79], v[78:79], v[226:227]
	v_pk_add_f32 v[72:73], v[72:73], v[228:229]
	v_pk_add_f32 v[74:75], v[74:75], v[230:231]
	v_pk_add_f32 v[68:69], v[68:69], v[232:233]
	v_pk_add_f32 v[70:71], v[70:71], v[234:235]
	v_pk_add_f32 v[64:65], v[64:65], v[236:237]
	v_pk_add_f32 v[66:67], v[66:67], v[238:239]
	v_mul_f32_e32 v224, v77, v77
	v_mul_f32_e32 v225, v79, v79
	v_mul_f32_e32 v226, v73, v73
	v_mul_f32_e32 v227, v75, v75
	v_mul_f32_e32 v228, v69, v69
	v_mul_f32_e32 v229, v71, v71
	v_mul_f32_e32 v230, v65, v65
	v_mul_f32_e32 v231, v67, v67
	v_fmac_f32_e32 v224, v76, v76
	v_fmac_f32_e32 v225, v78, v78
	v_fmac_f32_e32 v226, v72, v72
	v_fmac_f32_e32 v227, v74, v74
	v_fmac_f32_e32 v228, v68, v68
	v_fmac_f32_e32 v229, v70, v70
	v_fmac_f32_e32 v230, v64, v64
	v_fmac_f32_e32 v231, v66, v66
	v_add_f32_e32 v224, v224, v225
	v_add_f32_e32 v226, v226, v227
	v_add_f32_e32 v228, v228, v229
	v_add_f32_e32 v224, v224, v226
	v_add_f32_e32 v224, v224, v228
	v_add_f32_e32 v230, v230, v231
	v_add_f32_e32 v149, v224, v230
	ds_bpermute_b32 v157, v144, v149
	s_waitcnt vmcnt(12)
	v_pk_add_f32 v[60:61], v[60:61], v[240:241]
	v_pk_add_f32 v[62:63], v[62:63], v[242:243]
	v_pk_add_f32 v[56:57], v[56:57], v[244:245]
	v_pk_add_f32 v[58:59], v[58:59], v[246:247]
	v_pk_add_f32 v[52:53], v[52:53], v[248:249]
	v_pk_add_f32 v[54:55], v[54:55], v[250:251]
	v_pk_add_f32 v[48:49], v[48:49], v[252:253]
	v_pk_add_f32 v[50:51], v[50:51], v[254:255]
	v_mul_f32_e32 v240, v61, v61
	v_mul_f32_e32 v241, v63, v63
	v_mul_f32_e32 v242, v57, v57
	v_mul_f32_e32 v243, v59, v59
	v_mul_f32_e32 v244, v53, v53
	v_mul_f32_e32 v245, v55, v55
	v_mul_f32_e32 v246, v49, v49
	v_mul_f32_e32 v247, v51, v51
	v_fmac_f32_e32 v240, v60, v60
	v_fmac_f32_e32 v241, v62, v62
	v_fmac_f32_e32 v242, v56, v56
	v_fmac_f32_e32 v243, v58, v58
	v_fmac_f32_e32 v244, v52, v52
	v_fmac_f32_e32 v245, v54, v54
	v_fmac_f32_e32 v246, v48, v48
	v_fmac_f32_e32 v247, v50, v50
	v_add_f32_e32 v240, v240, v241
	v_add_f32_e32 v242, v242, v243
	v_add_f32_e32 v244, v244, v245
	v_add_f32_e32 v240, v240, v242
	v_add_f32_e32 v240, v240, v244
	v_add_f32_e32 v246, v246, v247
	v_add_f32_e32 v150, v240, v246
	ds_bpermute_b32 v158, v144, v150
	s_waitcnt vmcnt(8)
	v_pk_add_f32 v[44:45], v[44:45], v[176:177]
	v_pk_add_f32 v[46:47], v[46:47], v[178:179]
	v_pk_add_f32 v[40:41], v[40:41], v[180:181]
	v_pk_add_f32 v[42:43], v[42:43], v[182:183]
	v_pk_add_f32 v[36:37], v[36:37], v[184:185]
	v_pk_add_f32 v[38:39], v[38:39], v[186:187]
	v_pk_add_f32 v[32:33], v[32:33], v[188:189]
	v_pk_add_f32 v[34:35], v[34:35], v[190:191]
	v_mul_f32_e32 v176, v45, v45
	v_mul_f32_e32 v177, v47, v47
	v_mul_f32_e32 v178, v41, v41
	v_mul_f32_e32 v179, v43, v43
	v_mul_f32_e32 v180, v37, v37
	v_mul_f32_e32 v181, v39, v39
	v_mul_f32_e32 v182, v33, v33
	v_mul_f32_e32 v183, v35, v35
	v_fmac_f32_e32 v176, v44, v44
	v_fmac_f32_e32 v177, v46, v46
	v_fmac_f32_e32 v178, v40, v40
	v_fmac_f32_e32 v179, v42, v42
	v_fmac_f32_e32 v180, v36, v36
	v_fmac_f32_e32 v181, v38, v38
	v_fmac_f32_e32 v182, v32, v32
	v_fmac_f32_e32 v183, v34, v34
	v_add_f32_e32 v176, v176, v177
	v_add_f32_e32 v178, v178, v179
	v_add_f32_e32 v180, v180, v181
	v_add_f32_e32 v176, v176, v178
	v_add_f32_e32 v176, v176, v180
	v_add_f32_e32 v182, v182, v183
	v_add_f32_e32 v151, v176, v182
	ds_bpermute_b32 v159, v144, v151
	s_waitcnt vmcnt(4)
	v_pk_add_f32 v[28:29], v[28:29], v[192:193]
	v_pk_add_f32 v[30:31], v[30:31], v[194:195]
	v_pk_add_f32 v[24:25], v[24:25], v[196:197]
	v_pk_add_f32 v[26:27], v[26:27], v[198:199]
	v_pk_add_f32 v[20:21], v[20:21], v[200:201]
	v_pk_add_f32 v[22:23], v[22:23], v[202:203]
	v_pk_add_f32 v[16:17], v[16:17], v[204:205]
	v_pk_add_f32 v[18:19], v[18:19], v[206:207]
	v_mul_f32_e32 v192, v29, v29
	v_mul_f32_e32 v193, v31, v31
	v_mul_f32_e32 v194, v25, v25
	v_mul_f32_e32 v195, v27, v27
	v_mul_f32_e32 v196, v21, v21
	v_mul_f32_e32 v197, v23, v23
	v_mul_f32_e32 v198, v17, v17
	v_mul_f32_e32 v199, v19, v19
	v_fmac_f32_e32 v192, v28, v28
	v_fmac_f32_e32 v193, v30, v30
	v_fmac_f32_e32 v194, v24, v24
	v_fmac_f32_e32 v195, v26, v26
	v_fmac_f32_e32 v196, v20, v20
	v_fmac_f32_e32 v197, v22, v22
	v_fmac_f32_e32 v198, v16, v16
	v_fmac_f32_e32 v199, v18, v18
	v_add_f32_e32 v192, v192, v193
	v_add_f32_e32 v194, v194, v195
	v_add_f32_e32 v196, v196, v197
	v_add_f32_e32 v192, v192, v194
	v_add_f32_e32 v192, v192, v196
	v_add_f32_e32 v198, v198, v199
	v_add_f32_e32 v152, v192, v198
	ds_bpermute_b32 v160, v144, v152
	s_waitcnt vmcnt(0)
	v_pk_add_f32 v[12:13], v[12:13], v[208:209]
	v_pk_add_f32 v[14:15], v[14:15], v[210:211]
	v_pk_add_f32 v[8:9], v[8:9], v[212:213]
	v_pk_add_f32 v[10:11], v[10:11], v[214:215]
	v_pk_add_f32 v[4:5], v[4:5], v[216:217]
	v_pk_add_f32 v[6:7], v[6:7], v[218:219]
	v_pk_add_f32 v[0:1], v[0:1], v[220:221]
	v_pk_add_f32 v[2:3], v[2:3], v[222:223]
	v_mul_f32_e32 v208, v13, v13
	v_mul_f32_e32 v209, v15, v15
	v_mul_f32_e32 v210, v9, v9
	v_mul_f32_e32 v211, v11, v11
	v_mul_f32_e32 v212, v5, v5
	v_mul_f32_e32 v213, v7, v7
	v_mul_f32_e32 v214, v1, v1
	v_mul_f32_e32 v215, v3, v3
	v_fmac_f32_e32 v208, v12, v12
	v_fmac_f32_e32 v209, v14, v14
	v_fmac_f32_e32 v210, v8, v8
	v_fmac_f32_e32 v211, v10, v10
	v_fmac_f32_e32 v212, v4, v4
	v_fmac_f32_e32 v213, v6, v6
	v_fmac_f32_e32 v214, v0, v0
	v_fmac_f32_e32 v215, v2, v2
	v_add_f32_e32 v208, v208, v209
	v_add_f32_e32 v210, v210, v211
	v_add_f32_e32 v212, v212, v213
	v_add_f32_e32 v208, v208, v210
	v_add_f32_e32 v208, v208, v212
	v_add_f32_e32 v214, v214, v215
	v_add_f32_e32 v153, v208, v214
	ds_bpermute_b32 v161, v144, v153
	s_waitcnt lgkmcnt(0)
	v_add_f32_e32 v146, v146, v154
	v_add_f32_e32 v147, v147, v155
	v_add_f32_e32 v148, v148, v156
	v_add_f32_e32 v149, v149, v157
	v_add_f32_e32 v150, v150, v158
	v_add_f32_e32 v151, v151, v159
	v_add_f32_e32 v152, v152, v160
	v_add_f32_e32 v153, v153, v161
	ds_bpermute_b32 v154, v145, v146
	ds_bpermute_b32 v155, v145, v147
	ds_bpermute_b32 v156, v145, v148
	ds_bpermute_b32 v157, v145, v149
	ds_bpermute_b32 v158, v145, v150
	ds_bpermute_b32 v159, v145, v151
	ds_bpermute_b32 v160, v145, v152
	ds_bpermute_b32 v161, v145, v153
	s_and_saveexec_b64 s[42:43], s[0:1]
	s_waitcnt lgkmcnt(0)
	v_add_f32_e32 v146, v146, v154
	v_add_f32_e32 v147, v147, v155
	v_add_f32_e32 v148, v148, v156
	v_add_f32_e32 v149, v149, v157
	v_add_f32_e32 v150, v150, v158
	v_add_f32_e32 v151, v151, v159
	v_add_f32_e32 v152, v152, v160
	v_add_f32_e32 v153, v153, v161
	global_atomic_add_f32 v141, v146, s[10:11]
	global_atomic_add_f32 v141, v147, s[10:11] offset:64
	global_atomic_add_f32 v141, v148, s[10:11] offset:128
	global_atomic_add_f32 v141, v149, s[10:11] offset:192
	global_atomic_add_f32 v141, v150, s[10:11] offset:512
	global_atomic_add_f32 v141, v151, s[10:11] offset:576
	global_atomic_add_f32 v141, v152, s[10:11] offset:640
	global_atomic_add_f32 v141, v153, s[10:11] offset:704
	s_or_b64 exec, exec, s[42:43]
	global_load_dwordx4 v[176:179], v143, s[12:13]
	global_load_dwordx4 v[180:183], v143, s[12:13] offset:64
	global_load_dwordx4 v[184:187], v143, s[12:13] offset:512
	global_load_dwordx4 v[188:191], v143, s[12:13] offset:576
	s_lshl_b32 s8, s8, 7
	s_add_i32 s8, s8, s59
	s_ashr_i32 s9, s8, 31
	s_waitcnt vmcnt(0)
	s_lshl_b64 s[8:9], s[8:9], 2
	s_add_u32 s8, s64, s8
	s_addc_u32 s9, s65, s9
	s_and_saveexec_b64 s[42:43], s[4:5]
	s_cbranch_execz .LBB0_507
	s_mov_b64 s[44:45], exec
	v_mbcnt_lo_u32_b32 v160, s44, 0
	v_mbcnt_hi_u32_b32 v160, s45, v160
	v_cmp_eq_u32_e32 vcc, 0, v160
	s_and_b64 s[46:47], exec, vcc
	s_mov_b64 exec, s[46:47]
	s_cbranch_execz .LBB0_507
	s_bcnt1_i32_b64 s35, s[44:45]
	v_mov_b32_e32 v160, s35
	global_atomic_add v129, v160, s[8:9]

.LBB0_515:
	global_load_dword v192, v141, s[10:11] sc1
	global_load_dword v193, v141, s[10:11] offset:64 sc1
	global_load_dword v194, v141, s[10:11] offset:128 sc1
	global_load_dword v195, v141, s[10:11] offset:192 sc1
	global_load_dword v196, v141, s[10:11] offset:512 sc1
	global_load_dword v197, v141, s[10:11] offset:576 sc1
	global_load_dword v198, v141, s[10:11] offset:640 sc1
	global_load_dword v199, v141, s[10:11] offset:704 sc1
	s_waitcnt vmcnt(0)
	v_fmamk_f32 v192, v192, 0x3a800000, v169
	v_mul_f32_e32 v200, 0x4f800000, v192
	v_cmp_gt_f32_e32 vcc, s68, v192
	s_nop 1
	v_cndmask_b32_e32 v192, v192, v200, vcc
	v_sqrt_f32_e32 v200, v192
	s_nop 0
	v_add_u32_e32 v201, -1, v200
	v_add_u32_e32 v202, 1, v200
	v_fma_f32 v203, -v201, v200, v192
	v_fma_f32 v204, -v202, v200, v192
	v_cmp_ge_f32_e64 s[8:9], 0, v203
	s_nop 1
	v_cndmask_b32_e64 v200, v200, v201, s[8:9]
	v_cmp_lt_f32_e64 s[8:9], 0, v204
	s_nop 1
	v_cndmask_b32_e64 v200, v200, v202, s[8:9]
	v_mul_f32_e32 v201, 0x37800000, v200
	v_cndmask_b32_e32 v200, v200, v201, vcc
	v_cmp_class_f32_e32 vcc, v192, v170
	s_nop 1
	v_cndmask_b32_e32 v192, v200, v192, vcc
	v_div_scale_f32 v202, s[8:9], v192, v192, 1.0
	v_rcp_f32_e32 v203, v202
	v_div_scale_f32 v200, vcc, 1.0, v192, 1.0
	v_fma_f32 v201, -v202, v203, 1.0
	v_fmac_f32_e32 v203, v201, v203
	v_mul_f32_e32 v201, v200, v203
	v_fma_f32 v204, -v202, v201, v200
	v_fmac_f32_e32 v201, v204, v203
	v_fma_f32 v200, -v202, v201, v200
	v_div_fmas_f32 v200, v200, v203, v201
	v_div_fixup_f32 v206, v200, v192, 1.0
	v_pk_mul_f32 v[124:125], v[124:125], v[206:207] op_sel_hi:[1,0]
	v_pk_mul_f32 v[126:127], v[126:127], v[206:207] op_sel_hi:[1,0]
	v_pk_mul_f32 v[124:125], v[176:177], v[124:125]
	v_pk_mul_f32 v[126:127], v[178:179], v[126:127]
	global_store_dwordx4 v142, v[124:127], s[14:15] nt
	v_pk_mul_f32 v[120:121], v[120:121], v[206:207] op_sel_hi:[1,0]
	v_pk_mul_f32 v[122:123], v[122:123], v[206:207] op_sel_hi:[1,0]
	v_pk_mul_f32 v[120:121], v[180:181], v[120:121]
	v_pk_mul_f32 v[122:123], v[182:183], v[122:123]
	global_store_dwordx4 v142, v[120:123], s[14:15] offset:64 nt
	v_pk_mul_f32 v[116:117], v[116:117], v[206:207] op_sel_hi:[1,0]
	v_pk_mul_f32 v[118:119], v[118:119], v[206:207] op_sel_hi:[1,0]
	v_pk_mul_f32 v[116:117], v[184:185], v[116:117]
	v_pk_mul_f32 v[118:119], v[186:187], v[118:119]
	global_store_dwordx4 v142, v[116:119], s[14:15] offset:512 nt
	v_pk_mul_f32 v[112:113], v[112:113], v[206:207] op_sel_hi:[1,0]
	v_pk_mul_f32 v[114:115], v[114:115], v[206:207] op_sel_hi:[1,0]
	v_pk_mul_f32 v[112:113], v[188:189], v[112:113]
	v_pk_mul_f32 v[114:115], v[190:191], v[114:115]
	global_store_dwordx4 v142, v[112:115], s[14:15] offset:576 nt
	v_fmamk_f32 v193, v193, 0x3a800000, v169
	v_mul_f32_e32 v200, 0x4f800000, v193
	v_cmp_gt_f32_e32 vcc, s68, v193
	s_nop 1
	v_cndmask_b32_e32 v193, v193, v200, vcc
	v_sqrt_f32_e32 v200, v193
	s_nop 0
	v_add_u32_e32 v201, -1, v200
	v_add_u32_e32 v202, 1, v200
	v_fma_f32 v203, -v201, v200, v193
	v_fma_f32 v204, -v202, v200, v193
	v_cmp_ge_f32_e64 s[8:9], 0, v203
	s_nop 1
	v_cndmask_b32_e64 v200, v200, v201, s[8:9]
	v_cmp_lt_f32_e64 s[8:9], 0, v204
	s_nop 1
	v_cndmask_b32_e64 v200, v200, v202, s[8:9]
	v_mul_f32_e32 v201, 0x37800000, v200
	v_cndmask_b32_e32 v200, v200, v201, vcc
	v_cmp_class_f32_e32 vcc, v193, v170
	s_nop 1
	v_cndmask_b32_e32 v193, v200, v193, vcc
	v_div_scale_f32 v202, s[8:9], v193, v193, 1.0
	v_rcp_f32_e32 v203, v202
	v_div_scale_f32 v200, vcc, 1.0, v193, 1.0
	v_fma_f32 v201, -v202, v203, 1.0
	v_fmac_f32_e32 v203, v201, v203
	v_mul_f32_e32 v201, v200, v203
	v_fma_f32 v204, -v202, v201, v200
	v_fmac_f32_e32 v201, v204, v203
	v_fma_f32 v200, -v202, v201, v200
	v_div_fmas_f32 v200, v200, v203, v201
	v_div_fixup_f32 v206, v200, v193, 1.0
	s_add_u32 s100, s14, 0x10000
	s_addc_u32 s101, s15, 0
	v_pk_mul_f32 v[108:109], v[108:109], v[206:207] op_sel_hi:[1,0]
	v_pk_mul_f32 v[110:111], v[110:111], v[206:207] op_sel_hi:[1,0]
	v_pk_mul_f32 v[108:109], v[176:177], v[108:109]
	v_pk_mul_f32 v[110:111], v[178:179], v[110:111]
	global_store_dwordx4 v142, v[108:111], s[100:101] nt
	v_pk_mul_f32 v[104:105], v[104:105], v[206:207] op_sel_hi:[1,0]
	v_pk_mul_f32 v[106:107], v[106:107], v[206:207] op_sel_hi:[1,0]
	v_pk_mul_f32 v[104:105], v[180:181], v[104:105]
	v_pk_mul_f32 v[106:107], v[182:183], v[106:107]
	global_store_dwordx4 v142, v[104:107], s[100:101] offset:64 nt
	v_pk_mul_f32 v[100:101], v[100:101], v[206:207] op_sel_hi:[1,0]
	v_pk_mul_f32 v[102:103], v[102:103], v[206:207] op_sel_hi:[1,0]
	v_pk_mul_f32 v[100:101], v[184:185], v[100:101]
	v_pk_mul_f32 v[102:103], v[186:187], v[102:103]
	global_store_dwordx4 v142, v[100:103], s[100:101] offset:512 nt
	v_pk_mul_f32 v[96:97], v[96:97], v[206:207] op_sel_hi:[1,0]
	v_pk_mul_f32 v[98:99], v[98:99], v[206:207] op_sel_hi:[1,0]
	v_pk_mul_f32 v[96:97], v[188:189], v[96:97]
	v_pk_mul_f32 v[98:99], v[190:191], v[98:99]
	global_store_dwordx4 v142, v[96:99], s[100:101] offset:576 nt
	v_fmamk_f32 v194, v194, 0x3a800000, v169
	v_mul_f32_e32 v200, 0x4f800000, v194
	v_cmp_gt_f32_e32 vcc, s68, v194
	s_nop 1
	v_cndmask_b32_e32 v194, v194, v200, vcc
	v_sqrt_f32_e32 v200, v194
	s_nop 0
	v_add_u32_e32 v201, -1, v200
	v_add_u32_e32 v202, 1, v200
	v_fma_f32 v203, -v201, v200, v194
	v_fma_f32 v204, -v202, v200, v194
	v_cmp_ge_f32_e64 s[8:9], 0, v203
	s_nop 1
	v_cndmask_b32_e64 v200, v200, v201, s[8:9]
	v_cmp_lt_f32_e64 s[8:9], 0, v204
	s_nop 1
	v_cndmask_b32_e64 v200, v200, v202, s[8:9]
	v_mul_f32_e32 v201, 0x37800000, v200
	v_cndmask_b32_e32 v200, v200, v201, vcc
	v_cmp_class_f32_e32 vcc, v194, v170
	s_nop 1
	v_cndmask_b32_e32 v194, v200, v194, vcc
	v_div_scale_f32 v202, s[8:9], v194, v194, 1.0
	v_rcp_f32_e32 v203, v202
	v_div_scale_f32 v200, vcc, 1.0, v194, 1.0
	v_fma_f32 v201, -v202, v203, 1.0
	v_fmac_f32_e32 v203, v201, v203
	v_mul_f32_e32 v201, v200, v203
	v_fma_f32 v204, -v202, v201, v200
	v_fmac_f32_e32 v201, v204, v203
	v_fma_f32 v200, -v202, v201, v200
	v_div_fmas_f32 v200, v200, v203, v201
	v_div_fixup_f32 v206, v200, v194, 1.0
	s_add_u32 s100, s14, 0x20000
	s_addc_u32 s101, s15, 0
	v_pk_mul_f32 v[92:93], v[92:93], v[206:207] op_sel_hi:[1,0]
	v_pk_mul_f32 v[94:95], v[94:95], v[206:207] op_sel_hi:[1,0]
	v_pk_mul_f32 v[92:93], v[176:177], v[92:93]
	v_pk_mul_f32 v[94:95], v[178:179], v[94:95]
	global_store_dwordx4 v142, v[92:95], s[100:101] nt
	v_pk_mul_f32 v[88:89], v[88:89], v[206:207] op_sel_hi:[1,0]
	v_pk_mul_f32 v[90:91], v[90:91], v[206:207] op_sel_hi:[1,0]
	v_pk_mul_f32 v[88:89], v[180:181], v[88:89]
	v_pk_mul_f32 v[90:91], v[182:183], v[90:91]
	global_store_dwordx4 v142, v[88:91], s[100:101] offset:64 nt
	v_pk_mul_f32 v[84:85], v[84:85], v[206:207] op_sel_hi:[1,0]
	v_pk_mul_f32 v[86:87], v[86:87], v[206:207] op_sel_hi:[1,0]
	v_pk_mul_f32 v[84:85], v[184:185], v[84:85]
	v_pk_mul_f32 v[86:87], v[186:187], v[86:87]
	global_store_dwordx4 v142, v[84:87], s[100:101] offset:512 nt
	v_pk_mul_f32 v[80:81], v[80:81], v[206:207] op_sel_hi:[1,0]
	v_pk_mul_f32 v[82:83], v[82:83], v[206:207] op_sel_hi:[1,0]
	v_pk_mul_f32 v[80:81], v[188:189], v[80:81]
	v_pk_mul_f32 v[82:83], v[190:191], v[82:83]
	global_store_dwordx4 v142, v[80:83], s[100:101] offset:576 nt
	v_fmamk_f32 v195, v195, 0x3a800000, v169
	v_mul_f32_e32 v200, 0x4f800000, v195
	v_cmp_gt_f32_e32 vcc, s68, v195
	s_nop 1
	v_cndmask_b32_e32 v195, v195, v200, vcc
	v_sqrt_f32_e32 v200, v195
	s_nop 0
	v_add_u32_e32 v201, -1, v200
	v_add_u32_e32 v202, 1, v200
	v_fma_f32 v203, -v201, v200, v195
	v_fma_f32 v204, -v202, v200, v195
	v_cmp_ge_f32_e64 s[8:9], 0, v203
	s_nop 1
	v_cndmask_b32_e64 v200, v200, v201, s[8:9]
	v_cmp_lt_f32_e64 s[8:9], 0, v204
	s_nop 1
	v_cndmask_b32_e64 v200, v200, v202, s[8:9]
	v_mul_f32_e32 v201, 0x37800000, v200
	v_cndmask_b32_e32 v200, v200, v201, vcc
	v_cmp_class_f32_e32 vcc, v195, v170
	s_nop 1
	v_cndmask_b32_e32 v195, v200, v195, vcc
	v_div_scale_f32 v202, s[8:9], v195, v195, 1.0
	v_rcp_f32_e32 v203, v202
	v_div_scale_f32 v200, vcc, 1.0, v195, 1.0
	v_fma_f32 v201, -v202, v203, 1.0
	v_fmac_f32_e32 v203, v201, v203
	v_mul_f32_e32 v201, v200, v203
	v_fma_f32 v204, -v202, v201, v200
	v_fmac_f32_e32 v201, v204, v203
	v_fma_f32 v200, -v202, v201, v200
	v_div_fmas_f32 v200, v200, v203, v201
	v_div_fixup_f32 v206, v200, v195, 1.0
	s_add_u32 s100, s14, 0x30000
	s_addc_u32 s101, s15, 0
	v_pk_mul_f32 v[76:77], v[76:77], v[206:207] op_sel_hi:[1,0]
	v_pk_mul_f32 v[78:79], v[78:79], v[206:207] op_sel_hi:[1,0]
	v_pk_mul_f32 v[76:77], v[176:177], v[76:77]
	v_pk_mul_f32 v[78:79], v[178:179], v[78:79]
	global_store_dwordx4 v142, v[76:79], s[100:101] nt
	v_pk_mul_f32 v[72:73], v[72:73], v[206:207] op_sel_hi:[1,0]
	v_pk_mul_f32 v[74:75], v[74:75], v[206:207] op_sel_hi:[1,0]
	v_pk_mul_f32 v[72:73], v[180:181], v[72:73]
	v_pk_mul_f32 v[74:75], v[182:183], v[74:75]
	global_store_dwordx4 v142, v[72:75], s[100:101] offset:64 nt
	v_pk_mul_f32 v[68:69], v[68:69], v[206:207] op_sel_hi:[1,0]
	v_pk_mul_f32 v[70:71], v[70:71], v[206:207] op_sel_hi:[1,0]
	v_pk_mul_f32 v[68:69], v[184:185], v[68:69]
	v_pk_mul_f32 v[70:71], v[186:187], v[70:71]
	global_store_dwordx4 v142, v[68:71], s[100:101] offset:512 nt
	v_pk_mul_f32 v[64:65], v[64:65], v[206:207] op_sel_hi:[1,0]
	v_pk_mul_f32 v[66:67], v[66:67], v[206:207] op_sel_hi:[1,0]
	v_pk_mul_f32 v[64:65], v[188:189], v[64:65]
	v_pk_mul_f32 v[66:67], v[190:191], v[66:67]
	global_store_dwordx4 v142, v[64:67], s[100:101] offset:576 nt
	v_fmamk_f32 v196, v196, 0x3a800000, v169
	v_mul_f32_e32 v200, 0x4f800000, v196
	v_cmp_gt_f32_e32 vcc, s68, v196
	s_nop 1
	v_cndmask_b32_e32 v196, v196, v200, vcc
	v_sqrt_f32_e32 v200, v196
	s_nop 0
	v_add_u32_e32 v201, -1, v200
	v_add_u32_e32 v202, 1, v200
	v_fma_f32 v203, -v201, v200, v196
	v_fma_f32 v204, -v202, v200, v196
	v_cmp_ge_f32_e64 s[8:9], 0, v203
	s_nop 1
	v_cndmask_b32_e64 v200, v200, v201, s[8:9]
	v_cmp_lt_f32_e64 s[8:9], 0, v204
	s_nop 1
	v_cndmask_b32_e64 v200, v200, v202, s[8:9]
	v_mul_f32_e32 v201, 0x37800000, v200
	v_cndmask_b32_e32 v200, v200, v201, vcc
	v_cmp_class_f32_e32 vcc, v196, v170
	s_nop 1
	v_cndmask_b32_e32 v196, v200, v196, vcc
	v_div_scale_f32 v202, s[8:9], v196, v196, 1.0
	v_rcp_f32_e32 v203, v202
	v_div_scale_f32 v200, vcc, 1.0, v196, 1.0
	v_fma_f32 v201, -v202, v203, 1.0
	v_fmac_f32_e32 v203, v201, v203
	v_mul_f32_e32 v201, v200, v203
	v_fma_f32 v204, -v202, v201, v200
	v_fmac_f32_e32 v201, v204, v203
	v_fma_f32 v200, -v202, v201, v200
	v_div_fmas_f32 v200, v200, v203, v201
	v_div_fixup_f32 v206, v200, v196, 1.0
	s_add_u32 s100, s14, 0x80000
	s_addc_u32 s101, s15, 0
	v_pk_mul_f32 v[60:61], v[60:61], v[206:207] op_sel_hi:[1,0]
	v_pk_mul_f32 v[62:63], v[62:63], v[206:207] op_sel_hi:[1,0]
	v_pk_mul_f32 v[60:61], v[176:177], v[60:61]
	v_pk_mul_f32 v[62:63], v[178:179], v[62:63]
	global_store_dwordx4 v142, v[60:63], s[100:101] nt
	v_pk_mul_f32 v[56:57], v[56:57], v[206:207] op_sel_hi:[1,0]
	v_pk_mul_f32 v[58:59], v[58:59], v[206:207] op_sel_hi:[1,0]
	v_pk_mul_f32 v[56:57], v[180:181], v[56:57]
	v_pk_mul_f32 v[58:59], v[182:183], v[58:59]
	global_store_dwordx4 v142, v[56:59], s[100:101] offset:64 nt
	v_pk_mul_f32 v[52:53], v[52:53], v[206:207] op_sel_hi:[1,0]
	v_pk_mul_f32 v[54:55], v[54:55], v[206:207] op_sel_hi:[1,0]
	v_pk_mul_f32 v[52:53], v[184:185], v[52:53]
	v_pk_mul_f32 v[54:55], v[186:187], v[54:55]
	global_store_dwordx4 v142, v[52:55], s[100:101] offset:512 nt
	v_pk_mul_f32 v[48:49], v[48:49], v[206:207] op_sel_hi:[1,0]
	v_pk_mul_f32 v[50:51], v[50:51], v[206:207] op_sel_hi:[1,0]
	v_pk_mul_f32 v[48:49], v[188:189], v[48:49]
	v_pk_mul_f32 v[50:51], v[190:191], v[50:51]
	global_store_dwordx4 v142, v[48:51], s[100:101] offset:576 nt
	v_fmamk_f32 v197, v197, 0x3a800000, v169
	v_mul_f32_e32 v200, 0x4f800000, v197
	v_cmp_gt_f32_e32 vcc, s68, v197
	s_nop 1
	v_cndmask_b32_e32 v197, v197, v200, vcc
	v_sqrt_f32_e32 v200, v197
	s_nop 0
	v_add_u32_e32 v201, -1, v200
	v_add_u32_e32 v202, 1, v200
	v_fma_f32 v203, -v201, v200, v197
	v_fma_f32 v204, -v202, v200, v197
	v_cmp_ge_f32_e64 s[8:9], 0, v203
	s_nop 1
	v_cndmask_b32_e64 v200, v200, v201, s[8:9]
	v_cmp_lt_f32_e64 s[8:9], 0, v204
	s_nop 1
	v_cndmask_b32_e64 v200, v200, v202, s[8:9]
	v_mul_f32_e32 v201, 0x37800000, v200
	v_cndmask_b32_e32 v200, v200, v201, vcc
	v_cmp_class_f32_e32 vcc, v197, v170
	s_nop 1
	v_cndmask_b32_e32 v197, v200, v197, vcc
	v_div_scale_f32 v202, s[8:9], v197, v197, 1.0
	v_rcp_f32_e32 v203, v202
	v_div_scale_f32 v200, vcc, 1.0, v197, 1.0
	v_fma_f32 v201, -v202, v203, 1.0
	v_fmac_f32_e32 v203, v201, v203
	v_mul_f32_e32 v201, v200, v203
	v_fma_f32 v204, -v202, v201, v200
	v_fmac_f32_e32 v201, v204, v203
	v_fma_f32 v200, -v202, v201, v200
	v_div_fmas_f32 v200, v200, v203, v201
	v_div_fixup_f32 v206, v200, v197, 1.0
	s_add_u32 s100, s14, 0x90000
	s_addc_u32 s101, s15, 0
	v_pk_mul_f32 v[44:45], v[44:45], v[206:207] op_sel_hi:[1,0]
	v_pk_mul_f32 v[46:47], v[46:47], v[206:207] op_sel_hi:[1,0]
	v_pk_mul_f32 v[44:45], v[176:177], v[44:45]
	v_pk_mul_f32 v[46:47], v[178:179], v[46:47]
	global_store_dwordx4 v142, v[44:47], s[100:101] nt
	v_pk_mul_f32 v[40:41], v[40:41], v[206:207] op_sel_hi:[1,0]
	v_pk_mul_f32 v[42:43], v[42:43], v[206:207] op_sel_hi:[1,0]
	v_pk_mul_f32 v[40:41], v[180:181], v[40:41]
	v_pk_mul_f32 v[42:43], v[182:183], v[42:43]
	global_store_dwordx4 v142, v[40:43], s[100:101] offset:64 nt
	v_pk_mul_f32 v[36:37], v[36:37], v[206:207] op_sel_hi:[1,0]
	v_pk_mul_f32 v[38:39], v[38:39], v[206:207] op_sel_hi:[1,0]
	v_pk_mul_f32 v[36:37], v[184:185], v[36:37]
	v_pk_mul_f32 v[38:39], v[186:187], v[38:39]
	global_store_dwordx4 v142, v[36:39], s[100:101] offset:512 nt
	v_pk_mul_f32 v[32:33], v[32:33], v[206:207] op_sel_hi:[1,0]
	v_pk_mul_f32 v[34:35], v[34:35], v[206:207] op_sel_hi:[1,0]
	v_pk_mul_f32 v[32:33], v[188:189], v[32:33]
	v_pk_mul_f32 v[34:35], v[190:191], v[34:35]
	global_store_dwordx4 v142, v[32:35], s[100:101] offset:576 nt
	v_fmamk_f32 v198, v198, 0x3a800000, v169
	v_mul_f32_e32 v200, 0x4f800000, v198
	v_cmp_gt_f32_e32 vcc, s68, v198
	s_nop 1
	v_cndmask_b32_e32 v198, v198, v200, vcc
	v_sqrt_f32_e32 v200, v198
	s_nop 0
	v_add_u32_e32 v201, -1, v200
	v_add_u32_e32 v202, 1, v200
	v_fma_f32 v203, -v201, v200, v198
	v_fma_f32 v204, -v202, v200, v198
	v_cmp_ge_f32_e64 s[8:9], 0, v203
	s_nop 1
	v_cndmask_b32_e64 v200, v200, v201, s[8:9]
	v_cmp_lt_f32_e64 s[8:9], 0, v204
	s_nop 1
	v_cndmask_b32_e64 v200, v200, v202, s[8:9]
	v_mul_f32_e32 v201, 0x37800000, v200
	v_cndmask_b32_e32 v200, v200, v201, vcc
	v_cmp_class_f32_e32 vcc, v198, v170
	s_nop 1
	v_cndmask_b32_e32 v198, v200, v198, vcc
	v_div_scale_f32 v202, s[8:9], v198, v198, 1.0
	v_rcp_f32_e32 v203, v202
	v_div_scale_f32 v200, vcc, 1.0, v198, 1.0
	v_fma_f32 v201, -v202, v203, 1.0
	v_fmac_f32_e32 v203, v201, v203
	v_mul_f32_e32 v201, v200, v203
	v_fma_f32 v204, -v202, v201, v200
	v_fmac_f32_e32 v201, v204, v203
	v_fma_f32 v200, -v202, v201, v200
	v_div_fmas_f32 v200, v200, v203, v201
	v_div_fixup_f32 v206, v200, v198, 1.0
	s_add_u32 s100, s14, 0xa0000
	s_addc_u32 s101, s15, 0
	v_pk_mul_f32 v[28:29], v[28:29], v[206:207] op_sel_hi:[1,0]
	v_pk_mul_f32 v[30:31], v[30:31], v[206:207] op_sel_hi:[1,0]
	v_pk_mul_f32 v[28:29], v[176:177], v[28:29]
	v_pk_mul_f32 v[30:31], v[178:179], v[30:31]
	global_store_dwordx4 v142, v[28:31], s[100:101] nt
	v_pk_mul_f32 v[24:25], v[24:25], v[206:207] op_sel_hi:[1,0]
	v_pk_mul_f32 v[26:27], v[26:27], v[206:207] op_sel_hi:[1,0]
	v_pk_mul_f32 v[24:25], v[180:181], v[24:25]
	v_pk_mul_f32 v[26:27], v[182:183], v[26:27]
	global_store_dwordx4 v142, v[24:27], s[100:101] offset:64 nt
	v_pk_mul_f32 v[20:21], v[20:21], v[206:207] op_sel_hi:[1,0]
	v_pk_mul_f32 v[22:23], v[22:23], v[206:207] op_sel_hi:[1,0]
	v_pk_mul_f32 v[20:21], v[184:185], v[20:21]
	v_pk_mul_f32 v[22:23], v[186:187], v[22:23]
	global_store_dwordx4 v142, v[20:23], s[100:101] offset:512 nt
	v_pk_mul_f32 v[16:17], v[16:17], v[206:207] op_sel_hi:[1,0]
	v_pk_mul_f32 v[18:19], v[18:19], v[206:207] op_sel_hi:[1,0]
	v_pk_mul_f32 v[16:17], v[188:189], v[16:17]
	v_pk_mul_f32 v[18:19], v[190:191], v[18:19]
	global_store_dwordx4 v142, v[16:19], s[100:101] offset:576 nt
	v_fmamk_f32 v199, v199, 0x3a800000, v169
	v_mul_f32_e32 v200, 0x4f800000, v199
	v_cmp_gt_f32_e32 vcc, s68, v199
	s_nop 1
	v_cndmask_b32_e32 v199, v199, v200, vcc
	v_sqrt_f32_e32 v200, v199
	s_nop 0
	v_add_u32_e32 v201, -1, v200
	v_add_u32_e32 v202, 1, v200
	v_fma_f32 v203, -v201, v200, v199
	v_fma_f32 v204, -v202, v200, v199
	v_cmp_ge_f32_e64 s[8:9], 0, v203
	s_nop 1
	v_cndmask_b32_e64 v200, v200, v201, s[8:9]
	v_cmp_lt_f32_e64 s[8:9], 0, v204
	s_nop 1
	v_cndmask_b32_e64 v200, v200, v202, s[8:9]
	v_mul_f32_e32 v201, 0x37800000, v200
	v_cndmask_b32_e32 v200, v200, v201, vcc
	v_cmp_class_f32_e32 vcc, v199, v170
	s_nop 1
	v_cndmask_b32_e32 v199, v200, v199, vcc
	v_div_scale_f32 v202, s[8:9], v199, v199, 1.0
	v_rcp_f32_e32 v203, v202
	v_div_scale_f32 v200, vcc, 1.0, v199, 1.0
	v_fma_f32 v201, -v202, v203, 1.0
	v_fmac_f32_e32 v203, v201, v203
	v_mul_f32_e32 v201, v200, v203
	v_fma_f32 v204, -v202, v201, v200
	v_fmac_f32_e32 v201, v204, v203
	v_fma_f32 v200, -v202, v201, v200
	v_div_fmas_f32 v200, v200, v203, v201
	v_div_fixup_f32 v206, v200, v199, 1.0
	s_add_u32 s100, s14, 0xb0000
	s_addc_u32 s101, s15, 0
	v_pk_mul_f32 v[12:13], v[12:13], v[206:207] op_sel_hi:[1,0]
	v_pk_mul_f32 v[14:15], v[14:15], v[206:207] op_sel_hi:[1,0]
	v_pk_mul_f32 v[12:13], v[176:177], v[12:13]
	v_pk_mul_f32 v[14:15], v[178:179], v[14:15]
	global_store_dwordx4 v142, v[12:15], s[100:101] nt
	v_pk_mul_f32 v[8:9], v[8:9], v[206:207] op_sel_hi:[1,0]
	v_pk_mul_f32 v[10:11], v[10:11], v[206:207] op_sel_hi:[1,0]
	v_pk_mul_f32 v[8:9], v[180:181], v[8:9]
	v_pk_mul_f32 v[10:11], v[182:183], v[10:11]
	global_store_dwordx4 v142, v[8:11], s[100:101] offset:64 nt
	v_pk_mul_f32 v[4:5], v[4:5], v[206:207] op_sel_hi:[1,0]
	v_pk_mul_f32 v[6:7], v[6:7], v[206:207] op_sel_hi:[1,0]
	v_pk_mul_f32 v[4:5], v[184:185], v[4:5]
	v_pk_mul_f32 v[6:7], v[186:187], v[6:7]
	global_store_dwordx4 v142, v[4:7], s[100:101] offset:512 nt
	v_pk_mul_f32 v[0:1], v[0:1], v[206:207] op_sel_hi:[1,0]
	v_pk_mul_f32 v[2:3], v[2:3], v[206:207] op_sel_hi:[1,0]
	v_pk_mul_f32 v[0:1], v[188:189], v[0:1]
	v_pk_mul_f32 v[2:3], v[190:191], v[2:3]
	global_store_dwordx4 v142, v[0:3], s[100:101] offset:576 nt
	s_andn2_b64 vcc, exec, s[6:7]
	s_mov_b64 s[6:7], -1
	s_cbranch_vccnz .LBB0_477
	s_andn2_b64 vcc, exec, s[20:21]
	s_cbranch_vccnz .LBB0_476
	s_barrier
	s_branch .LBB0_476

	.amdhsa_kernel _Z6mk_fwd4Args
		.amdhsa_group_segment_fixed_size 0
		.amdhsa_private_segment_fixed_size 0
		.amdhsa_kernarg_size 376
		.amdhsa_user_sgpr_count 2
		.amdhsa_user_sgpr_dispatch_ptr 0
		.amdhsa_user_sgpr_queue_ptr 0
		.amdhsa_user_sgpr_kernarg_segment_ptr 1
		.amdhsa_user_sgpr_dispatch_id 0
		.amdhsa_user_sgpr_kernarg_preload_length 0
		.amdhsa_user_sgpr_kernarg_preload_offset 0
		.amdhsa_user_sgpr_private_segment_size 0
		.amdhsa_uses_dynamic_stack 0
		.amdhsa_enable_private_segment 0
		.amdhsa_system_sgpr_workgroup_id_x 1
		.amdhsa_system_sgpr_workgroup_id_y 0
		.amdhsa_system_sgpr_workgroup_id_z 0
		.amdhsa_system_sgpr_workgroup_info 0
		.amdhsa_system_vgpr_workitem_id 2
		.amdhsa_next_free_vgpr 256
		.amdhsa_next_free_sgpr 102
		.amdhsa_accum_offset 256
		.amdhsa_reserve_vcc 1
		.amdhsa_float_round_mode_32 0
		.amdhsa_float_round_mode_16_64 0
		.amdhsa_float_denorm_mode_32 3
		.amdhsa_float_denorm_mode_16_64 3
		.amdhsa_dx10_clamp 1
		.amdhsa_ieee_mode 1
		.amdhsa_fp16_overflow 0
		.amdhsa_tg_split 0
		.amdhsa_exception_fp_ieee_invalid_op 0
		.amdhsa_exception_fp_denorm_src 0
		.amdhsa_exception_fp_ieee_div_zero 0
		.amdhsa_exception_fp_ieee_overflow 0
		.amdhsa_exception_fp_ieee_underflow 0
		.amdhsa_exception_fp_ieee_inexact 0
		.amdhsa_exception_int_div_zero 0
	.end_amdhsa_kernel

.Lfunc_end0:
	.size	_Z6mk_fwd4Args, .Lfunc_end0-_Z6mk_fwd4Args
	.set _Z6mk_fwd4Args.num_vgpr, 256
	.set _Z6mk_fwd4Args.num_agpr, 0
	.set _Z6mk_fwd4Args.numbered_sgpr, 100
	.set _Z6mk_fwd4Args.num_named_barrier, 0
	.set _Z6mk_fwd4Args.private_seg_size, 0
	.set _Z6mk_fwd4Args.uses_vcc, 1
	.set _Z6mk_fwd4Args.uses_flat_scratch, 0
	.set _Z6mk_fwd4Args.has_dyn_sized_stack, 0
	.set _Z6mk_fwd4Args.has_recursion, 0
	.set _Z6mk_fwd4Args.has_indirect_call, 0

amdhsa.kernels:
  - .agpr_count:     0
    .args:
      - .offset:         0
        .size:           120
        .value_kind:     by_value
      - .offset:         120
        .size:           4
        .value_kind:     hidden_block_count_x
      - .offset:         124
        .size:           4
        .value_kind:     hidden_block_count_y
      - .offset:         128
        .size:           4
        .value_kind:     hidden_block_count_z
      - .offset:         132
        .size:           2
        .value_kind:     hidden_group_size_x
      - .offset:         134
        .size:           2
        .value_kind:     hidden_group_size_y
      - .offset:         136
        .size:           2
        .value_kind:     hidden_group_size_z
      - .offset:         138
        .size:           2
        .value_kind:     hidden_remainder_x
      - .offset:         140
        .size:           2
        .value_kind:     hidden_remainder_y
      - .offset:         142
        .size:           2
        .value_kind:     hidden_remainder_z
      - .offset:         160
        .size:           8
        .value_kind:     hidden_global_offset_x
      - .offset:         168
        .size:           8
        .value_kind:     hidden_global_offset_y
      - .offset:         176
        .size:           8
        .value_kind:     hidden_global_offset_z
      - .offset:         184
        .size:           2
        .value_kind:     hidden_grid_dims
      - .offset:         208
        .size:           8
        .value_kind:     hidden_multigrid_sync_arg
      - .offset:         240
        .size:           4
        .value_kind:     hidden_dynamic_lds_size
    .group_segment_fixed_size: 0
    .kernarg_segment_align: 8
    .kernarg_segment_size: 376
    .language:       OpenCL C
    .language_version:
      - 2
      - 0
    .max_flat_workgroup_size: 512
    .name:           _Z6mk_fwd4Args
    .private_segment_fixed_size: 0
    .sgpr_count:     108
    .sgpr_spill_count: 0
    .symbol:         _Z6mk_fwd4Args.kd
    .uniform_work_group_size: 1
    .uses_dynamic_stack: false
    .vgpr_count:     256
    .vgpr_spill_count: 0
    .wavefront_size: 64
